# LoRA (decay / in-context-rate) GEMM epilogues: bias quads loaded once per tile, no per-group vmcnt drain
# speedup vs baseline: 1.0042x; 1.0042x over previous
; __device__ __forceinline__ float softplusf_(float x) { return x > 20.f ? x : __logf(1.f + __expf(x)); }
;     ...
;     const bf16_t* ap = A + (size_t)(m0 + lrow) * lda + lsw;
;     const bf16_t* bp = Wt + (size_t)(n0 + lrow) * K + lsw;
;     const size_t a32 = (size_t)32 * lda, b32 = (size_t)32 * K;
;     typedef __attribute__((address_space(3))) unsigned lds_u32;
;     lds_u32* sbase = (lds_u32*)(smem) + wave * 256;
;     ...
;     GLDS(ap, 0, 0, 0)
;     asm volatile("s_waitcnt vmcnt(0)" ::: "memory");
;     __syncthreads();
;     for (int kt = 0; kt < KT; kt++) {
;       const int cur = (kt & 1) * 16384;
;       if (kt + 1 < KT) {
;         const bf16_t* apx = ap;
;         int kc = (kt + 1) * 64;
;         if (SHIFT && kc >= 1024) { apx = ap - lda; kc -= 1024; }
;         const int nxt = ((kt + 1) & 1) * 16384;
;         GLDS(apx, kc, (kt + 1) * 64, nxt)
;       }
; #pragma unroll
;       for (int kk = 0; kk < 2; kk++) {
;         bf16x8 af[4], bfr[4];
;         const int csw = (((kk * 4 + fq) ^ fsw) << 3);
; #pragma unroll
;         for (int mi = 0; mi < 4; mi++) af[mi] = *(const bf16x8*)(smem + cur + (wm * 64 + mi * 16 + fr) * 64 + csw);
; #pragma unroll
;         for (int ni = 0; ni < 4; ni++) bfr[ni] = *(const bf16x8*)(smem + cur + 8192 + (wn * 64 + ni * 16 + fr) * 64 + csw);
; #pragma unroll
;         for (int mi = 0; mi < 4; mi++)
; #pragma unroll
;           for (int ni = 0; ni < 4; ni++)
;             acc[mi][ni] = TR ? __builtin_amdgcn_mfma_f32_16x16x32_bf16(bfr[ni], af[mi], acc[mi][ni], 0, 0, 0)
;                              : __builtin_amdgcn_mfma_f32_16x16x32_bf16(af[mi], bfr[ni], acc[mi][ni], 0, 0, 0);
;       }
;     ...
;             } else if constexpr (EPI == EPI_LW) {
;               const float4 w0v = *(const float4*)(e.v0 + col);
;               uint2 o;
;               o.x = pack2(__expf(-softplusf_(-(w0v.x + a[0])) - 0.5f), __expf(-softplusf_(-(w0v.y + a[1])) - 0.5f));
;               o.y = pack2(__expf(-softplusf_(-(w0v.z + a[2])) - 0.5f), __expf(-softplusf_(-(w0v.w + a[3])) - 0.5f));
;               *(uint2*)(e.b0 + (row * (unsigned)D + col)) = o;
.LBB0_584:
	s_lshl_b32 s0, s12, 7
	v_add_u32_e32 v8, s0, v80
	s_lshl_b32 s1, s9, 7
	v_mad_i64_i32 v[10:11], s[8:9], v8, s45, v[74:75]
	v_readfirstlane_b32 s8, v81
	s_mov_b32 m0, s8
	s_mov_b64 s[8:9], 0x5000
	v_add_u32_e32 v8, 0x1000, v81
	v_lshl_add_u64 v[14:15], v[10:11], 0, s[8:9]
	v_readfirstlane_b32 s8, v8
	global_load_lds_dwordx4 v[10:11], off
	s_mov_b32 m0, s8
	s_mov_b64 s[8:9], 0xa000
	v_add_u32_e32 v8, 0x2000, v81
	global_load_lds_dwordx4 v[14:15], off
	v_lshl_add_u64 v[14:15], v[10:11], 0, s[8:9]
	v_readfirstlane_b32 s8, v8
	v_add_u32_e32 v12, s1, v80
	s_mov_b32 m0, s8
	s_mov_b64 s[8:9], 0xf000
	v_add_u32_e32 v8, 0x3000, v81
	v_ashrrev_i32_e32 v13, 31, v12
	v_lshl_add_u64 v[10:11], v[10:11], 0, s[8:9]
	v_readfirstlane_b32 s8, v8
	v_add_u32_e32 v8, 0x4000, v81
	v_lshlrev_b64 v[12:13], 7, v[12:13]
	global_load_lds_dwordx4 v[14:15], off
	s_mov_b32 m0, s8
	v_readfirstlane_b32 s8, v8
	v_lshl_add_u64 v[12:13], v[76:77], 0, v[12:13]
	global_load_lds_dwordx4 v[10:11], off
	s_mov_b32 m0, s8
	s_mov_b64 s[8:9], 0x1000
	v_add_u32_e32 v8, 0x5000, v81
	v_lshl_add_u64 v[10:11], v[12:13], 0, s[8:9]
	v_readfirstlane_b32 s8, v8
	global_load_lds_dwordx4 v[12:13], off
	s_mov_b32 m0, s8
	s_mov_b64 s[8:9], 0x2000
	v_add_u32_e32 v8, 0x6000, v81
	global_load_lds_dwordx4 v[10:11], off
	v_lshl_add_u64 v[10:11], v[12:13], 0, s[8:9]
	v_readfirstlane_b32 s8, v8
	s_mov_b32 m0, s8
	s_mov_b64 s[8:9], 0x3000
	v_add_u32_e32 v8, 0x7000, v81
	global_load_lds_dwordx4 v[10:11], off
	v_lshl_add_u64 v[10:11], v[12:13], 0, s[8:9]
	v_readfirstlane_b32 s8, v8
	s_mov_b32 m0, s8
	v_or_b32_e32 v8, s1, v82
	v_lshl_add_u64 v[78:79], v[8:9], 2, s[78:79]
	global_load_dwordx4 v[166:169], v[78:79], off
	global_load_dwordx4 v[170:173], v[78:79], off offset:64
	global_load_dwordx4 v[174:177], v[78:79], off offset:128
	global_load_dwordx4 v[178:181], v[78:79], off offset:192
	global_load_lds_dwordx4 v[10:11], off
	s_waitcnt vmcnt(0)
	s_waitcnt vmcnt(0) lgkmcnt(0)
	s_barrier
	ds_read_b128 v[10:13], v84
	ds_read_b128 v[14:17], v84 offset:2048
	ds_read_b128 v[18:21], v84 offset:4096
	ds_read_b128 v[22:25], v84 offset:6144
	ds_read_b128 v[26:29], v85 offset:16384
	ds_read_b128 v[30:33], v85 offset:18432
	ds_read_b128 v[34:37], v85 offset:20480
	ds_read_b128 v[38:41], v85 offset:22528
	s_waitcnt lgkmcnt(3)
	v_mfma_f32_16x16x32_bf16 v[42:45], v[26:29], v[10:13], 0
	v_lshl_add_u64 v[78:79], v[8:9], 2, s[78:79]
	s_mov_b32 s14, 0x800000
	s_mov_b32 s16, 0x3f317217
	s_waitcnt lgkmcnt(2)
	v_mfma_f32_16x16x32_bf16 v[46:49], v[30:33], v[10:13], 0
	s_mov_b32 s17, 0x7f800000
	s_mov_b32 s15, 0xc1a00000
	v_readlane_b32 s12, v247, 25
	s_waitcnt lgkmcnt(1)
	v_mfma_f32_16x16x32_bf16 v[50:53], v[34:37], v[10:13], 0
	v_readlane_b32 s13, v247, 26
	v_mfma_f32_16x16x32_bf16 v[54:57], v[26:29], v[14:17], 0
	v_mfma_f32_16x16x32_bf16 v[88:91], v[30:33], v[14:17], 0
	v_mfma_f32_16x16x32_bf16 v[92:95], v[34:37], v[14:17], 0
	v_mfma_f32_16x16x32_bf16 v[96:99], v[26:29], v[18:21], 0
	v_mfma_f32_16x16x32_bf16 v[108:111], v[26:29], v[22:25], 0
	v_mfma_f32_16x16x32_bf16 v[112:115], v[30:33], v[22:25], 0
	v_mfma_f32_16x16x32_bf16 v[116:119], v[34:37], v[22:25], 0
	s_waitcnt lgkmcnt(0)
	v_mfma_f32_16x16x32_bf16 v[120:123], v[38:41], v[22:25], 0
	ds_read_b128 v[22:25], v86
	ds_read_b128 v[26:29], v86 offset:2048
	ds_read_b128 v[124:127], v86 offset:4096
	ds_read_b128 v[128:131], v86 offset:6144
	ds_read_b128 v[132:135], v87 offset:16384
	ds_read_b128 v[136:139], v87 offset:18432
	ds_read_b128 v[140:143], v87 offset:20480
	ds_read_b128 v[144:147], v87 offset:22528
	s_waitcnt vmcnt(0)
	s_waitcnt lgkmcnt(0)
	v_mfma_f32_16x16x32_bf16 v[66:69], v[136:139], v[22:25], v[46:49]
	s_barrier
	v_mfma_f32_16x16x32_bf16 v[62:65], v[140:143], v[22:25], v[50:53]
	v_mfma_f32_16x16x32_bf16 v[50:53], v[136:139], v[26:29], v[88:91]
	v_mfma_f32_16x16x32_bf16 v[46:49], v[140:143], v[26:29], v[92:95]
	s_nop 1
	v_add_lshl_u32 v88, v83, s0, 10
	v_mfma_f32_16x16x32_bf16 v[70:73], v[132:135], v[22:25], v[42:45]
	v_mfma_f32_16x16x32_bf16 v[10:13], v[38:41], v[10:13], 0
	v_mfma_f32_16x16x32_bf16 v[58:61], v[144:147], v[22:25], v[10:13]
	v_mov_b32_e32 v90, v166
	v_mov_b32_e32 v91, v167
	v_mov_b32_e32 v92, v168
	v_mov_b32_e32 v93, v169
	s_nop 4
	v_add_f32_e32 v70, v70, v90
	v_mul_f32_e32 v89, 0xbfb8aa3b, v70
	v_exp_f32_e32 v89, v89
	v_cmp_gt_f32_e32 vcc, s15, v70
	v_add_f32_e32 v71, v71, v91
	v_mfma_f32_16x16x32_bf16 v[14:17], v[38:41], v[14:17], 0
	v_add_f32_e32 v89, 1.0, v89
	v_cmp_gt_f32_e64 s[0:1], s14, v89
	v_mfma_f32_16x16x32_bf16 v[100:103], v[30:33], v[18:21], 0
	s_nop 0
	v_cndmask_b32_e64 v90, 0, 32, s[0:1]
	v_ldexp_f32 v89, v89, v90
	v_log_f32_e32 v89, v89
	v_mfma_f32_16x16x32_bf16 v[104:107], v[34:37], v[18:21], 0
	v_mul_f32_e32 v90, 0x3f317217, v89
	v_fma_f32 v90, v89, s16, -v90
	v_fmac_f32_e32 v90, 0x3377d1cf, v89
	v_fmac_f32_e32 v90, 0x3f317217, v89
	v_cmp_lt_f32_e64 s[8:9], |v89|, s17
	v_mfma_f32_16x16x32_bf16 v[18:21], v[38:41], v[18:21], 0
	s_nop 0
	v_cndmask_b32_e64 v89, v89, v90, s[8:9]
	v_cndmask_b32_e64 v90, 0, v213, s[0:1]
	v_sub_f32_e32 v89, v89, v90
	v_cndmask_b32_e64 v70, v89, -v70, vcc
	v_mul_f32_e32 v89, 0xbfb8aa3b, v71
	v_exp_f32_e32 v89, v89
	v_cmp_gt_f32_e32 vcc, s15, v71
	v_sub_f32_e32 v70, -0.5, v70
	v_mul_f32_e32 v70, 0x3fb8aa3b, v70
	v_add_f32_e32 v89, 1.0, v89
	v_cmp_gt_f32_e64 s[0:1], s14, v89
	v_exp_f32_e32 v70, v70
	v_mfma_f32_16x16x32_bf16 v[54:57], v[132:135], v[26:29], v[54:57]
	v_cndmask_b32_e64 v90, 0, 32, s[0:1]
	v_ldexp_f32 v89, v89, v90
	v_log_f32_e32 v89, v89
	v_mfma_f32_16x16x32_bf16 v[42:45], v[144:147], v[26:29], v[14:17]
	v_mul_f32_e32 v90, 0x3f317217, v89
	v_fma_f32 v90, v89, s16, -v90
; __device__ __forceinline__ float softplusf_(float x) { return x > 20.f ? x : __logf(1.f + __expf(x)); }
;     ...
;             } else if constexpr (EPI == EPI_LW) {
;               const float4 w0v = *(const float4*)(e.v0 + col);
;               uint2 o;
;               o.x = pack2(__expf(-softplusf_(-(w0v.x + a[0])) - 0.5f), __expf(-softplusf_(-(w0v.y + a[1])) - 0.5f));
;               o.y = pack2(__expf(-softplusf_(-(w0v.z + a[2])) - 0.5f), __expf(-softplusf_(-(w0v.w + a[3])) - 0.5f));
;               *(uint2*)(e.b0 + (row * (unsigned)D + col)) = o;
	v_fmac_f32_e32 v90, 0x3377d1cf, v89
	v_fmac_f32_e32 v90, 0x3f317217, v89
	v_cmp_lt_f32_e64 s[8:9], |v89|, s17
	v_mfma_f32_16x16x32_bf16 v[38:41], v[132:135], v[124:127], v[96:99]
	s_nop 0
	v_cndmask_b32_e64 v89, v89, v90, s[8:9]
	v_cndmask_b32_e64 v90, 0, v213, s[0:1]
	v_sub_f32_e32 v89, v89, v90
	v_cndmask_b32_e64 v71, v89, -v71, vcc
	v_sub_f32_e32 v71, -0.5, v71
	v_mul_f32_e32 v71, 0x3fb8aa3b, v71
	v_exp_f32_e32 v71, v71
	v_mfma_f32_16x16x32_bf16 v[34:37], v[136:139], v[124:127], v[100:103]
	v_cvt_pk_bf16_f32 v70, v70, v71
	v_add_f32_e32 v71, v72, v92
	v_mul_f32_e32 v72, 0xbfb8aa3b, v71
	v_exp_f32_e32 v72, v72
	v_cmp_gt_f32_e32 vcc, s15, v71
	v_mfma_f32_16x16x32_bf16 v[30:33], v[140:143], v[124:127], v[104:107]
	v_add_f32_e32 v72, 1.0, v72
	v_cmp_gt_f32_e64 s[0:1], s14, v72
	v_mfma_f32_16x16x32_bf16 v[26:29], v[144:147], v[124:127], v[18:21]
	s_nop 0
	v_cndmask_b32_e64 v89, 0, 32, s[0:1]
	v_ldexp_f32 v72, v72, v89
	v_log_f32_e32 v72, v72
	v_mfma_f32_16x16x32_bf16 v[22:25], v[132:135], v[128:131], v[108:111]
	v_mul_f32_e32 v89, 0x3f317217, v72
	v_fma_f32 v89, v72, s16, -v89
	v_fmac_f32_e32 v89, 0x3377d1cf, v72
	v_fmac_f32_e32 v89, 0x3f317217, v72
	v_cmp_lt_f32_e64 s[8:9], |v72|, s17
	v_mfma_f32_16x16x32_bf16 v[18:21], v[136:139], v[128:131], v[112:115]
	s_nop 0
	v_cndmask_b32_e64 v72, v72, v89, s[8:9]
	v_cndmask_b32_e64 v89, 0, v213, s[0:1]
	v_sub_f32_e32 v72, v72, v89
	v_cndmask_b32_e64 v71, v72, -v71, vcc
	v_add_f32_e32 v72, v73, v93
	v_mul_f32_e32 v73, 0xbfb8aa3b, v72
	v_exp_f32_e32 v73, v73
	v_cmp_gt_f32_e32 vcc, s15, v72
	v_sub_f32_e32 v71, -0.5, v71
	v_mul_f32_e32 v71, 0x3fb8aa3b, v71
	v_add_f32_e32 v73, 1.0, v73
	v_cmp_gt_f32_e64 s[0:1], s14, v73
	v_exp_f32_e32 v71, v71
	v_mfma_f32_16x16x32_bf16 v[14:17], v[140:143], v[128:131], v[116:119]
	v_cndmask_b32_e64 v89, 0, 32, s[0:1]
	v_ldexp_f32 v73, v73, v89
	v_log_f32_e32 v73, v73
	v_mfma_f32_16x16x32_bf16 v[10:13], v[144:147], v[128:131], v[120:123]
	v_mul_f32_e32 v89, 0x3f317217, v73
	v_fma_f32 v89, v73, s16, -v89
	v_fmac_f32_e32 v89, 0x3377d1cf, v73
	v_fmac_f32_e32 v89, 0x3f317217, v73
	v_cmp_lt_f32_e64 s[8:9], |v73|, s17
	s_nop 1
	v_cndmask_b32_e64 v73, v73, v89, s[8:9]
	v_cndmask_b32_e64 v89, 0, v213, s[0:1]
	v_sub_f32_e32 v73, v73, v89
	v_cndmask_b32_e64 v72, v73, -v72, vcc
	v_sub_f32_e32 v72, -0.5, v72
	v_mul_f32_e32 v72, 0x3fb8aa3b, v72
	v_exp_f32_e32 v72, v72
	v_mov_b32_e32 v73, v9
	v_cvt_pk_bf16_f32 v71, v71, v72
	v_add_u32_e32 v72, v88, v8
	v_lshl_add_u64 v[72:73], v[72:73], 1, s[12:13]
	global_store_dwordx2 v[72:73], v[70:71], off
	v_or_b32_e32 v71, 16, v8
	v_mov_b32_e32 v90, v170
	v_mov_b32_e32 v91, v171
	v_mov_b32_e32 v92, v172
	v_mov_b32_e32 v93, v173
	v_add_f32_e32 v66, v66, v90
	v_mul_f32_e32 v70, 0xbfb8aa3b, v66
	v_exp_f32_e32 v70, v70
	v_cmp_gt_f32_e32 vcc, s15, v66
	v_add_f32_e32 v67, v67, v91
	v_add_f32_e32 v70, 1.0, v70
	v_cmp_gt_f32_e64 s[0:1], s14, v70
	s_nop 1
	v_cndmask_b32_e64 v72, 0, 32, s[0:1]
	v_ldexp_f32 v70, v70, v72
	v_log_f32_e32 v70, v70
	s_nop 0
	v_mul_f32_e32 v72, 0x3f317217, v70
	v_fma_f32 v72, v70, s16, -v72
	v_fmac_f32_e32 v72, 0x3377d1cf, v70
	v_fmac_f32_e32 v72, 0x3f317217, v70
	v_cmp_lt_f32_e64 s[8:9], |v70|, s17
	s_nop 1
	v_cndmask_b32_e64 v70, v70, v72, s[8:9]
	v_cndmask_b32_e64 v72, 0, v213, s[0:1]
	v_sub_f32_e32 v70, v70, v72
	v_cndmask_b32_e64 v66, v70, -v66, vcc
	v_mul_f32_e32 v70, 0xbfb8aa3b, v67
	v_exp_f32_e32 v70, v70
	v_cmp_gt_f32_e32 vcc, s15, v67
	v_sub_f32_e32 v66, -0.5, v66
	v_mul_f32_e32 v66, 0x3fb8aa3b, v66
	v_add_f32_e32 v70, 1.0, v70
	v_cmp_gt_f32_e64 s[0:1], s14, v70
	v_exp_f32_e32 v66, v66
	s_nop 0
	v_cndmask_b32_e64 v72, 0, 32, s[0:1]
	v_ldexp_f32 v70, v70, v72
	v_log_f32_e32 v70, v70
	s_nop 0
	v_mul_f32_e32 v72, 0x3f317217, v70
	v_fma_f32 v72, v70, s16, -v72
	v_fmac_f32_e32 v72, 0x3377d1cf, v70
	v_fmac_f32_e32 v72, 0x3f317217, v70
	v_cmp_lt_f32_e64 s[8:9], |v70|, s17
	s_nop 1
	v_cndmask_b32_e64 v70, v70, v72, s[8:9]
	v_cndmask_b32_e64 v72, 0, v213, s[0:1]
	v_sub_f32_e32 v70, v70, v72
	v_cndmask_b32_e64 v67, v70, -v67, vcc
	v_sub_f32_e32 v67, -0.5, v67
	v_mul_f32_e32 v67, 0x3fb8aa3b, v67
	v_exp_f32_e32 v67, v67
	s_nop 0
	v_cvt_pk_bf16_f32 v66, v66, v67
	v_add_f32_e32 v67, v68, v92
	v_mul_f32_e32 v68, 0xbfb8aa3b, v67
	v_exp_f32_e32 v68, v68
	v_cmp_gt_f32_e32 vcc, s15, v67
	v_add_f32_e32 v68, 1.0, v68
	v_cmp_gt_f32_e64 s[0:1], s14, v68
	s_nop 1
	v_cndmask_b32_e64 v70, 0, 32, s[0:1]
	v_ldexp_f32 v68, v68, v70
	v_log_f32_e32 v68, v68
	s_nop 0
	v_mul_f32_e32 v70, 0x3f317217, v68
	v_fma_f32 v70, v68, s16, -v70
	v_fmac_f32_e32 v70, 0x3377d1cf, v68
	v_fmac_f32_e32 v70, 0x3f317217, v68
	v_cmp_lt_f32_e64 s[8:9], |v68|, s17
	s_nop 1
	v_cndmask_b32_e64 v68, v68, v70, s[8:9]
	v_cndmask_b32_e64 v70, 0, v213, s[0:1]
	v_sub_f32_e32 v68, v68, v70
	v_cndmask_b32_e64 v67, v68, -v67, vcc
	v_add_f32_e32 v68, v69, v93
	v_mul_f32_e32 v69, 0xbfb8aa3b, v68
	v_exp_f32_e32 v69, v69
	v_cmp_gt_f32_e32 vcc, s15, v68
	v_sub_f32_e32 v67, -0.5, v67
	v_mul_f32_e32 v67, 0x3fb8aa3b, v67
	v_add_f32_e32 v69, 1.0, v69
	v_cmp_gt_f32_e64 s[0:1], s14, v69
	v_exp_f32_e32 v67, v67
	s_nop 0
	v_cndmask_b32_e64 v70, 0, 32, s[0:1]
	v_ldexp_f32 v69, v69, v70
	v_log_f32_e32 v69, v69
	s_nop 0
	v_mul_f32_e32 v70, 0x3f317217, v69
	v_fma_f32 v70, v69, s16, -v70
	v_fmac_f32_e32 v70, 0x3377d1cf, v69
	v_fmac_f32_e32 v70, 0x3f317217, v69
	v_cmp_lt_f32_e64 s[8:9], |v69|, s17
	s_nop 1
	v_cndmask_b32_e64 v69, v69, v70, s[8:9]
	v_cndmask_b32_e64 v70, 0, v213, s[0:1]
	v_sub_f32_e32 v69, v69, v70
	v_cndmask_b32_e64 v68, v69, -v68, vcc
	v_sub_f32_e32 v68, -0.5, v68
	v_mul_f32_e32 v68, 0x3fb8aa3b, v68
	v_exp_f32_e32 v68, v68
	v_mov_b32_e32 v69, v9
	v_or_b32_e32 v70, 32, v8
; __device__ __forceinline__ float softplusf_(float x) { return x > 20.f ? x : __logf(1.f + __expf(x)); }
;     ...
;             } else if constexpr (EPI == EPI_LW) {
;               const float4 w0v = *(const float4*)(e.v0 + col);
;               uint2 o;
;               o.x = pack2(__expf(-softplusf_(-(w0v.x + a[0])) - 0.5f), __expf(-softplusf_(-(w0v.y + a[1])) - 0.5f));
;               o.y = pack2(__expf(-softplusf_(-(w0v.z + a[2])) - 0.5f), __expf(-softplusf_(-(w0v.w + a[3])) - 0.5f));
;               *(uint2*)(e.b0 + (row * (unsigned)D + col)) = o;
	v_cvt_pk_bf16_f32 v67, v67, v68
	v_add_u32_e32 v68, v88, v71
	v_lshl_add_u64 v[68:69], v[68:69], 1, s[12:13]
	global_store_dwordx2 v[68:69], v[66:67], off
	v_mov_b32_e32 v66, v174
	v_mov_b32_e32 v67, v175
	v_mov_b32_e32 v68, v176
	v_mov_b32_e32 v69, v177
	v_add_f32_e32 v62, v62, v66
	v_mul_f32_e32 v66, 0xbfb8aa3b, v62
	v_exp_f32_e32 v66, v66
	v_cmp_gt_f32_e32 vcc, s15, v62
	v_add_f32_e32 v63, v63, v67
	v_add_f32_e32 v66, 1.0, v66
	v_cmp_gt_f32_e64 s[0:1], s14, v66
	s_nop 1
	v_cndmask_b32_e64 v72, 0, 32, s[0:1]
	v_ldexp_f32 v66, v66, v72
	v_log_f32_e32 v66, v66
	s_nop 0
	v_mul_f32_e32 v72, 0x3f317217, v66
	v_fma_f32 v72, v66, s16, -v72
	v_fmac_f32_e32 v72, 0x3377d1cf, v66
	v_fmac_f32_e32 v72, 0x3f317217, v66
	v_cmp_lt_f32_e64 s[8:9], |v66|, s17
	s_nop 1
	v_cndmask_b32_e64 v66, v66, v72, s[8:9]
	v_cndmask_b32_e64 v72, 0, v213, s[0:1]
	v_sub_f32_e32 v66, v66, v72
	v_cndmask_b32_e64 v62, v66, -v62, vcc
	v_mul_f32_e32 v66, 0xbfb8aa3b, v63
	v_exp_f32_e32 v66, v66
	v_cmp_gt_f32_e32 vcc, s15, v63
	v_sub_f32_e32 v62, -0.5, v62
	v_mul_f32_e32 v62, 0x3fb8aa3b, v62
	v_add_f32_e32 v66, 1.0, v66
	v_cmp_gt_f32_e64 s[0:1], s14, v66
	v_exp_f32_e32 v62, v62
	s_nop 0
	v_cndmask_b32_e64 v67, 0, 32, s[0:1]
	v_ldexp_f32 v66, v66, v67
	v_log_f32_e32 v66, v66
	s_nop 0
	v_mul_f32_e32 v67, 0x3f317217, v66
	v_fma_f32 v67, v66, s16, -v67
	v_fmac_f32_e32 v67, 0x3377d1cf, v66
	v_fmac_f32_e32 v67, 0x3f317217, v66
	v_cmp_lt_f32_e64 s[8:9], |v66|, s17
	s_nop 1
	v_cndmask_b32_e64 v66, v66, v67, s[8:9]
	v_cndmask_b32_e64 v67, 0, v213, s[0:1]
	v_sub_f32_e32 v66, v66, v67
	v_cndmask_b32_e64 v63, v66, -v63, vcc
	v_sub_f32_e32 v63, -0.5, v63
	v_mul_f32_e32 v63, 0x3fb8aa3b, v63
	v_exp_f32_e32 v63, v63
	s_nop 0
	v_cvt_pk_bf16_f32 v62, v62, v63
	v_add_f32_e32 v63, v64, v68
	v_mul_f32_e32 v64, 0xbfb8aa3b, v63
	v_exp_f32_e32 v64, v64
	v_cmp_gt_f32_e32 vcc, s15, v63
	v_add_f32_e32 v64, 1.0, v64
	v_cmp_gt_f32_e64 s[0:1], s14, v64
	s_nop 1
	v_cndmask_b32_e64 v66, 0, 32, s[0:1]
	v_ldexp_f32 v64, v64, v66
	v_log_f32_e32 v64, v64
	s_nop 0
	v_mul_f32_e32 v66, 0x3f317217, v64
	v_fma_f32 v66, v64, s16, -v66
	v_fmac_f32_e32 v66, 0x3377d1cf, v64
	v_fmac_f32_e32 v66, 0x3f317217, v64
	v_cmp_lt_f32_e64 s[8:9], |v64|, s17
	s_nop 1
	v_cndmask_b32_e64 v64, v64, v66, s[8:9]
	v_cndmask_b32_e64 v66, 0, v213, s[0:1]
	v_sub_f32_e32 v64, v64, v66
	v_cndmask_b32_e64 v63, v64, -v63, vcc
	v_add_f32_e32 v64, v65, v69
	v_mul_f32_e32 v65, 0xbfb8aa3b, v64
	v_exp_f32_e32 v65, v65
	v_cmp_gt_f32_e32 vcc, s15, v64
	v_sub_f32_e32 v63, -0.5, v63
	v_mul_f32_e32 v63, 0x3fb8aa3b, v63
	v_add_f32_e32 v65, 1.0, v65
	v_cmp_gt_f32_e64 s[0:1], s14, v65
	v_exp_f32_e32 v63, v63
	s_nop 0
	v_cndmask_b32_e64 v66, 0, 32, s[0:1]
	v_ldexp_f32 v65, v65, v66
	v_log_f32_e32 v65, v65
	s_nop 0
	v_mul_f32_e32 v66, 0x3f317217, v65
	v_fma_f32 v66, v65, s16, -v66
	v_fmac_f32_e32 v66, 0x3377d1cf, v65
	v_fmac_f32_e32 v66, 0x3f317217, v65
	v_cmp_lt_f32_e64 s[8:9], |v65|, s17
	s_nop 1
	v_cndmask_b32_e64 v65, v65, v66, s[8:9]
	v_cndmask_b32_e64 v66, 0, v213, s[0:1]
	v_sub_f32_e32 v65, v65, v66
	v_cndmask_b32_e64 v64, v65, -v64, vcc
	v_sub_f32_e32 v64, -0.5, v64
	v_mul_f32_e32 v64, 0x3fb8aa3b, v64
	v_exp_f32_e32 v64, v64
	v_mov_b32_e32 v65, v9
	v_or_b32_e32 v66, 48, v8
	v_cvt_pk_bf16_f32 v63, v63, v64
	v_add_u32_e32 v64, v88, v70
	v_lshl_add_u64 v[64:65], v[64:65], 1, s[12:13]
	global_store_dwordx2 v[64:65], v[62:63], off
	v_mov_b32_e32 v62, v178
	v_mov_b32_e32 v63, v179
	v_mov_b32_e32 v64, v180
	v_mov_b32_e32 v65, v181
	v_add_f32_e32 v58, v58, v62
	v_mul_f32_e32 v62, 0xbfb8aa3b, v58
	v_exp_f32_e32 v62, v62
	v_cmp_gt_f32_e32 vcc, s15, v58
	v_add_f32_e32 v59, v59, v63
	v_add_f32_e32 v62, 1.0, v62
	v_cmp_gt_f32_e64 s[0:1], s14, v62
	s_nop 1
	v_cndmask_b32_e64 v67, 0, 32, s[0:1]
	v_ldexp_f32 v62, v62, v67
	v_log_f32_e32 v62, v62
	s_nop 0
	v_mul_f32_e32 v67, 0x3f317217, v62
	v_fma_f32 v67, v62, s16, -v67
	v_fmac_f32_e32 v67, 0x3377d1cf, v62
	v_fmac_f32_e32 v67, 0x3f317217, v62
	v_cmp_lt_f32_e64 s[8:9], |v62|, s17
	s_nop 1
	v_cndmask_b32_e64 v62, v62, v67, s[8:9]
	v_cndmask_b32_e64 v67, 0, v213, s[0:1]
	v_sub_f32_e32 v62, v62, v67
	v_cndmask_b32_e64 v58, v62, -v58, vcc
	v_mul_f32_e32 v62, 0xbfb8aa3b, v59
	v_exp_f32_e32 v62, v62
	v_cmp_gt_f32_e32 vcc, s15, v59
	v_sub_f32_e32 v58, -0.5, v58
	v_mul_f32_e32 v58, 0x3fb8aa3b, v58
	v_add_f32_e32 v62, 1.0, v62
	v_cmp_gt_f32_e64 s[0:1], s14, v62
	v_exp_f32_e32 v58, v58
	s_nop 0
	v_cndmask_b32_e64 v63, 0, 32, s[0:1]
	v_ldexp_f32 v62, v62, v63
	v_log_f32_e32 v62, v62
	s_nop 0
	v_mul_f32_e32 v63, 0x3f317217, v62
	v_fma_f32 v63, v62, s16, -v63
	v_fmac_f32_e32 v63, 0x3377d1cf, v62
	v_fmac_f32_e32 v63, 0x3f317217, v62
	v_cmp_lt_f32_e64 s[8:9], |v62|, s17
	s_nop 1
	v_cndmask_b32_e64 v62, v62, v63, s[8:9]
	v_cndmask_b32_e64 v63, 0, v213, s[0:1]
	v_sub_f32_e32 v62, v62, v63
	v_cndmask_b32_e64 v59, v62, -v59, vcc
	v_sub_f32_e32 v59, -0.5, v59
	v_mul_f32_e32 v59, 0x3fb8aa3b, v59
	v_exp_f32_e32 v59, v59
	s_nop 0
	v_cvt_pk_bf16_f32 v58, v58, v59
	v_add_f32_e32 v59, v60, v64
	v_mul_f32_e32 v60, 0xbfb8aa3b, v59
	v_exp_f32_e32 v60, v60
	v_cmp_gt_f32_e32 vcc, s15, v59
	v_add_f32_e32 v60, 1.0, v60
	v_cmp_gt_f32_e64 s[0:1], s14, v60
	s_nop 1
	v_cndmask_b32_e64 v62, 0, 32, s[0:1]
	v_ldexp_f32 v60, v60, v62
	v_log_f32_e32 v60, v60
	s_nop 0
	v_mul_f32_e32 v62, 0x3f317217, v60
	v_fma_f32 v62, v60, s16, -v62
	v_fmac_f32_e32 v62, 0x3377d1cf, v60
	v_fmac_f32_e32 v62, 0x3f317217, v60
	v_cmp_lt_f32_e64 s[8:9], |v60|, s17
	s_nop 1
	v_cndmask_b32_e64 v60, v60, v62, s[8:9]
	v_cndmask_b32_e64 v62, 0, v213, s[0:1]
	v_sub_f32_e32 v60, v60, v62
	v_cndmask_b32_e64 v59, v60, -v59, vcc
	v_add_f32_e32 v60, v61, v65
	v_mul_f32_e32 v61, 0xbfb8aa3b, v60
; __device__ __forceinline__ float softplusf_(float x) { return x > 20.f ? x : __logf(1.f + __expf(x)); }
;     ...
;             } else if constexpr (EPI == EPI_LW) {
;               const float4 w0v = *(const float4*)(e.v0 + col);
;               uint2 o;
;               o.x = pack2(__expf(-softplusf_(-(w0v.x + a[0])) - 0.5f), __expf(-softplusf_(-(w0v.y + a[1])) - 0.5f));
;               o.y = pack2(__expf(-softplusf_(-(w0v.z + a[2])) - 0.5f), __expf(-softplusf_(-(w0v.w + a[3])) - 0.5f));
;               *(uint2*)(e.b0 + (row * (unsigned)D + col)) = o;
	v_exp_f32_e32 v61, v61
	v_cmp_gt_f32_e32 vcc, s15, v60
	v_sub_f32_e32 v59, -0.5, v59
	v_mul_f32_e32 v59, 0x3fb8aa3b, v59
	v_add_f32_e32 v61, 1.0, v61
	v_cmp_gt_f32_e64 s[0:1], s14, v61
	v_exp_f32_e32 v59, v59
	s_nop 0
	v_cndmask_b32_e64 v62, 0, 32, s[0:1]
	v_ldexp_f32 v61, v61, v62
	v_log_f32_e32 v61, v61
	s_nop 0
	v_mul_f32_e32 v62, 0x3f317217, v61
	v_fma_f32 v62, v61, s16, -v62
	v_fmac_f32_e32 v62, 0x3377d1cf, v61
	v_fmac_f32_e32 v62, 0x3f317217, v61
	v_cmp_lt_f32_e64 s[8:9], |v61|, s17
	s_nop 1
	v_cndmask_b32_e64 v61, v61, v62, s[8:9]
	v_cndmask_b32_e64 v62, 0, v213, s[0:1]
	v_sub_f32_e32 v61, v61, v62
	v_cndmask_b32_e64 v60, v61, -v60, vcc
	v_sub_f32_e32 v60, -0.5, v60
	v_mul_f32_e32 v60, 0x3fb8aa3b, v60
	v_exp_f32_e32 v60, v60
	v_mov_b32_e32 v61, v9
	v_cvt_pk_bf16_f32 v59, v59, v60
	v_add_u32_e32 v60, v88, v66
	v_lshl_add_u64 v[60:61], v[60:61], 1, s[12:13]
	global_store_dwordx2 v[60:61], v[58:59], off
	v_or_b32_e32 v58, 0x4000, v88
	v_mov_b32_e32 v60, v166
	v_mov_b32_e32 v61, v167
	v_mov_b32_e32 v62, v168
	v_mov_b32_e32 v63, v169
	v_add_f32_e32 v54, v54, v60
	v_mul_f32_e32 v59, 0xbfb8aa3b, v54
	v_exp_f32_e32 v59, v59
	v_cmp_gt_f32_e32 vcc, s15, v54
	v_add_f32_e32 v55, v55, v61
	v_add_f32_e32 v59, 1.0, v59
	v_cmp_gt_f32_e64 s[0:1], s14, v59
	s_nop 1
	v_cndmask_b32_e64 v60, 0, 32, s[0:1]
	v_ldexp_f32 v59, v59, v60
	v_log_f32_e32 v59, v59
	s_nop 0
	v_mul_f32_e32 v60, 0x3f317217, v59
	v_fma_f32 v60, v59, s16, -v60
	v_fmac_f32_e32 v60, 0x3377d1cf, v59
	v_fmac_f32_e32 v60, 0x3f317217, v59
	v_cmp_lt_f32_e64 s[8:9], |v59|, s17
	s_nop 1
	v_cndmask_b32_e64 v59, v59, v60, s[8:9]
	v_cndmask_b32_e64 v60, 0, v213, s[0:1]
	v_sub_f32_e32 v59, v59, v60
	v_cndmask_b32_e64 v54, v59, -v54, vcc
	v_mul_f32_e32 v59, 0xbfb8aa3b, v55
	v_exp_f32_e32 v59, v59
	v_cmp_gt_f32_e32 vcc, s15, v55
	v_sub_f32_e32 v54, -0.5, v54
	v_mul_f32_e32 v54, 0x3fb8aa3b, v54
	v_add_f32_e32 v59, 1.0, v59
	v_cmp_gt_f32_e64 s[0:1], s14, v59
	v_exp_f32_e32 v54, v54
	s_nop 0
	v_cndmask_b32_e64 v60, 0, 32, s[0:1]
	v_ldexp_f32 v59, v59, v60
	v_log_f32_e32 v59, v59
	s_nop 0
	v_mul_f32_e32 v60, 0x3f317217, v59
	v_fma_f32 v60, v59, s16, -v60
	v_fmac_f32_e32 v60, 0x3377d1cf, v59
	v_fmac_f32_e32 v60, 0x3f317217, v59
	v_cmp_lt_f32_e64 s[8:9], |v59|, s17
	s_nop 1
	v_cndmask_b32_e64 v59, v59, v60, s[8:9]
	v_cndmask_b32_e64 v60, 0, v213, s[0:1]
	v_sub_f32_e32 v59, v59, v60
	v_cndmask_b32_e64 v55, v59, -v55, vcc
	v_sub_f32_e32 v55, -0.5, v55
	v_mul_f32_e32 v55, 0x3fb8aa3b, v55
	v_exp_f32_e32 v55, v55
	s_nop 0
	v_cvt_pk_bf16_f32 v54, v54, v55
	v_add_f32_e32 v55, v56, v62
	v_mul_f32_e32 v56, 0xbfb8aa3b, v55
	v_exp_f32_e32 v56, v56
	v_cmp_gt_f32_e32 vcc, s15, v55
	v_add_f32_e32 v56, 1.0, v56
	v_cmp_gt_f32_e64 s[0:1], s14, v56
	s_nop 1
	v_cndmask_b32_e64 v59, 0, 32, s[0:1]
	v_ldexp_f32 v56, v56, v59
	v_log_f32_e32 v56, v56
	s_nop 0
	v_mul_f32_e32 v59, 0x3f317217, v56
	v_fma_f32 v59, v56, s16, -v59
	v_fmac_f32_e32 v59, 0x3377d1cf, v56
	v_fmac_f32_e32 v59, 0x3f317217, v56
	v_cmp_lt_f32_e64 s[8:9], |v56|, s17
	s_nop 1
	v_cndmask_b32_e64 v56, v56, v59, s[8:9]
	v_cndmask_b32_e64 v59, 0, v213, s[0:1]
	v_sub_f32_e32 v56, v56, v59
	v_cndmask_b32_e64 v55, v56, -v55, vcc
	v_add_f32_e32 v56, v57, v63
	v_mul_f32_e32 v57, 0xbfb8aa3b, v56
	v_exp_f32_e32 v57, v57
	v_cmp_gt_f32_e32 vcc, s15, v56
	v_sub_f32_e32 v55, -0.5, v55
	v_mul_f32_e32 v55, 0x3fb8aa3b, v55
	v_add_f32_e32 v57, 1.0, v57
	v_cmp_gt_f32_e64 s[0:1], s14, v57
	v_exp_f32_e32 v55, v55
	s_nop 0
	v_cndmask_b32_e64 v59, 0, 32, s[0:1]
	v_ldexp_f32 v57, v57, v59
	v_log_f32_e32 v57, v57
	s_nop 0
	v_mul_f32_e32 v59, 0x3f317217, v57
	v_fma_f32 v59, v57, s16, -v59
	v_fmac_f32_e32 v59, 0x3377d1cf, v57
	v_fmac_f32_e32 v59, 0x3f317217, v57
	v_cmp_lt_f32_e64 s[8:9], |v57|, s17
	s_nop 1
	v_cndmask_b32_e64 v57, v57, v59, s[8:9]
	v_cndmask_b32_e64 v59, 0, v213, s[0:1]
	v_sub_f32_e32 v57, v57, v59
	v_cndmask_b32_e64 v56, v57, -v56, vcc
	v_sub_f32_e32 v56, -0.5, v56
	v_mul_f32_e32 v56, 0x3fb8aa3b, v56
	v_exp_f32_e32 v56, v56
	v_mov_b32_e32 v57, v9
	v_cvt_pk_bf16_f32 v55, v55, v56
	v_add_u32_e32 v56, v58, v8
	v_lshl_add_u64 v[56:57], v[56:57], 1, s[12:13]
	global_store_dwordx2 v[56:57], v[54:55], off
	v_mov_b32_e32 v54, v170
	v_mov_b32_e32 v55, v171
	v_mov_b32_e32 v56, v172
	v_mov_b32_e32 v57, v173
	v_add_f32_e32 v50, v50, v54
	v_mul_f32_e32 v54, 0xbfb8aa3b, v50
	v_exp_f32_e32 v54, v54
	v_cmp_gt_f32_e32 vcc, s15, v50
	v_add_f32_e32 v51, v51, v55
	v_add_f32_e32 v54, 1.0, v54
	v_cmp_gt_f32_e64 s[0:1], s14, v54
	s_nop 1
	v_cndmask_b32_e64 v59, 0, 32, s[0:1]
	v_ldexp_f32 v54, v54, v59
	v_log_f32_e32 v54, v54
	s_nop 0
	v_mul_f32_e32 v59, 0x3f317217, v54
	v_fma_f32 v59, v54, s16, -v59
	v_fmac_f32_e32 v59, 0x3377d1cf, v54
	v_fmac_f32_e32 v59, 0x3f317217, v54
	v_cmp_lt_f32_e64 s[8:9], |v54|, s17
	s_nop 1
	v_cndmask_b32_e64 v54, v54, v59, s[8:9]
	v_cndmask_b32_e64 v59, 0, v213, s[0:1]
	v_sub_f32_e32 v54, v54, v59
	v_cndmask_b32_e64 v50, v54, -v50, vcc
	v_mul_f32_e32 v54, 0xbfb8aa3b, v51
	v_exp_f32_e32 v54, v54
	v_cmp_gt_f32_e32 vcc, s15, v51
	v_sub_f32_e32 v50, -0.5, v50
	v_mul_f32_e32 v50, 0x3fb8aa3b, v50
	v_add_f32_e32 v54, 1.0, v54
	v_cmp_gt_f32_e64 s[0:1], s14, v54
	v_exp_f32_e32 v50, v50
	s_nop 0
	v_cndmask_b32_e64 v55, 0, 32, s[0:1]
	v_ldexp_f32 v54, v54, v55
	v_log_f32_e32 v54, v54
	s_nop 0
	v_mul_f32_e32 v55, 0x3f317217, v54
	v_fma_f32 v55, v54, s16, -v55
	v_fmac_f32_e32 v55, 0x3377d1cf, v54
	v_fmac_f32_e32 v55, 0x3f317217, v54
	v_cmp_lt_f32_e64 s[8:9], |v54|, s17
	s_nop 1
	v_cndmask_b32_e64 v54, v54, v55, s[8:9]
	v_cndmask_b32_e64 v55, 0, v213, s[0:1]
	v_sub_f32_e32 v54, v54, v55
	v_cndmask_b32_e64 v51, v54, -v51, vcc
	v_sub_f32_e32 v51, -0.5, v51
	v_mul_f32_e32 v51, 0x3fb8aa3b, v51
; __device__ __forceinline__ float softplusf_(float x) { return x > 20.f ? x : __logf(1.f + __expf(x)); }
;     ...
;             } else if constexpr (EPI == EPI_LW) {
;               const float4 w0v = *(const float4*)(e.v0 + col);
;               uint2 o;
;               o.x = pack2(__expf(-softplusf_(-(w0v.x + a[0])) - 0.5f), __expf(-softplusf_(-(w0v.y + a[1])) - 0.5f));
;               o.y = pack2(__expf(-softplusf_(-(w0v.z + a[2])) - 0.5f), __expf(-softplusf_(-(w0v.w + a[3])) - 0.5f));
;               *(uint2*)(e.b0 + (row * (unsigned)D + col)) = o;
	v_exp_f32_e32 v51, v51
	s_nop 0
	v_cvt_pk_bf16_f32 v50, v50, v51
	v_add_f32_e32 v51, v52, v56
	v_mul_f32_e32 v52, 0xbfb8aa3b, v51
	v_exp_f32_e32 v52, v52
	v_cmp_gt_f32_e32 vcc, s15, v51
	v_add_f32_e32 v52, 1.0, v52
	v_cmp_gt_f32_e64 s[0:1], s14, v52
	s_nop 1
	v_cndmask_b32_e64 v54, 0, 32, s[0:1]
	v_ldexp_f32 v52, v52, v54
	v_log_f32_e32 v52, v52
	s_nop 0
	v_mul_f32_e32 v54, 0x3f317217, v52
	v_fma_f32 v54, v52, s16, -v54
	v_fmac_f32_e32 v54, 0x3377d1cf, v52
	v_fmac_f32_e32 v54, 0x3f317217, v52
	v_cmp_lt_f32_e64 s[8:9], |v52|, s17
	s_nop 1
	v_cndmask_b32_e64 v52, v52, v54, s[8:9]
	v_cndmask_b32_e64 v54, 0, v213, s[0:1]
	v_sub_f32_e32 v52, v52, v54
	v_cndmask_b32_e64 v51, v52, -v51, vcc
	v_add_f32_e32 v52, v53, v57
	v_mul_f32_e32 v53, 0xbfb8aa3b, v52
	v_exp_f32_e32 v53, v53
	v_cmp_gt_f32_e32 vcc, s15, v52
	v_sub_f32_e32 v51, -0.5, v51
	v_mul_f32_e32 v51, 0x3fb8aa3b, v51
	v_add_f32_e32 v53, 1.0, v53
	v_cmp_gt_f32_e64 s[0:1], s14, v53
	v_exp_f32_e32 v51, v51
	s_nop 0
	v_cndmask_b32_e64 v54, 0, 32, s[0:1]
	v_ldexp_f32 v53, v53, v54
	v_log_f32_e32 v53, v53
	s_nop 0
	v_mul_f32_e32 v54, 0x3f317217, v53
	v_fma_f32 v54, v53, s16, -v54
	v_fmac_f32_e32 v54, 0x3377d1cf, v53
	v_fmac_f32_e32 v54, 0x3f317217, v53
	v_cmp_lt_f32_e64 s[8:9], |v53|, s17
	s_nop 1
	v_cndmask_b32_e64 v53, v53, v54, s[8:9]
	v_cndmask_b32_e64 v54, 0, v213, s[0:1]
	v_sub_f32_e32 v53, v53, v54
	v_cndmask_b32_e64 v52, v53, -v52, vcc
	v_sub_f32_e32 v52, -0.5, v52
	v_mul_f32_e32 v52, 0x3fb8aa3b, v52
	v_exp_f32_e32 v52, v52
	v_mov_b32_e32 v53, v9
	v_cvt_pk_bf16_f32 v51, v51, v52
	v_add_u32_e32 v52, v58, v71
	v_lshl_add_u64 v[52:53], v[52:53], 1, s[12:13]
	global_store_dwordx2 v[52:53], v[50:51], off
	v_mov_b32_e32 v50, v174
	v_mov_b32_e32 v51, v175
	v_mov_b32_e32 v52, v176
	v_mov_b32_e32 v53, v177
	v_add_f32_e32 v46, v46, v50
	v_mul_f32_e32 v50, 0xbfb8aa3b, v46
	v_exp_f32_e32 v50, v50
	v_cmp_gt_f32_e32 vcc, s15, v46
	v_add_f32_e32 v47, v47, v51
	v_add_f32_e32 v50, 1.0, v50
	v_cmp_gt_f32_e64 s[0:1], s14, v50
	s_nop 1
	v_cndmask_b32_e64 v54, 0, 32, s[0:1]
	v_ldexp_f32 v50, v50, v54
	v_log_f32_e32 v50, v50
	s_nop 0
	v_mul_f32_e32 v54, 0x3f317217, v50
	v_fma_f32 v54, v50, s16, -v54
	v_fmac_f32_e32 v54, 0x3377d1cf, v50
	v_fmac_f32_e32 v54, 0x3f317217, v50
	v_cmp_lt_f32_e64 s[8:9], |v50|, s17
	s_nop 1
	v_cndmask_b32_e64 v50, v50, v54, s[8:9]
	v_cndmask_b32_e64 v54, 0, v213, s[0:1]
	v_sub_f32_e32 v50, v50, v54
	v_cndmask_b32_e64 v46, v50, -v46, vcc
	v_mul_f32_e32 v50, 0xbfb8aa3b, v47
	v_exp_f32_e32 v50, v50
	v_cmp_gt_f32_e32 vcc, s15, v47
	v_sub_f32_e32 v46, -0.5, v46
	v_mul_f32_e32 v46, 0x3fb8aa3b, v46
	v_add_f32_e32 v50, 1.0, v50
	v_cmp_gt_f32_e64 s[0:1], s14, v50
	v_exp_f32_e32 v46, v46
	s_nop 0
	v_cndmask_b32_e64 v51, 0, 32, s[0:1]
	v_ldexp_f32 v50, v50, v51
	v_log_f32_e32 v50, v50
	s_nop 0
	v_mul_f32_e32 v51, 0x3f317217, v50
	v_fma_f32 v51, v50, s16, -v51
	v_fmac_f32_e32 v51, 0x3377d1cf, v50
	v_fmac_f32_e32 v51, 0x3f317217, v50
	v_cmp_lt_f32_e64 s[8:9], |v50|, s17
	s_nop 1
	v_cndmask_b32_e64 v50, v50, v51, s[8:9]
	v_cndmask_b32_e64 v51, 0, v213, s[0:1]
	v_sub_f32_e32 v50, v50, v51
	v_cndmask_b32_e64 v47, v50, -v47, vcc
	v_sub_f32_e32 v47, -0.5, v47
	v_mul_f32_e32 v47, 0x3fb8aa3b, v47
	v_exp_f32_e32 v47, v47
	s_nop 0
	v_cvt_pk_bf16_f32 v46, v46, v47
	v_add_f32_e32 v47, v48, v52
	v_mul_f32_e32 v48, 0xbfb8aa3b, v47
	v_exp_f32_e32 v48, v48
	v_cmp_gt_f32_e32 vcc, s15, v47
	v_add_f32_e32 v48, 1.0, v48
	v_cmp_gt_f32_e64 s[0:1], s14, v48
	s_nop 1
	v_cndmask_b32_e64 v50, 0, 32, s[0:1]
	v_ldexp_f32 v48, v48, v50
	v_log_f32_e32 v48, v48
	s_nop 0
	v_mul_f32_e32 v50, 0x3f317217, v48
	v_fma_f32 v50, v48, s16, -v50
	v_fmac_f32_e32 v50, 0x3377d1cf, v48
	v_fmac_f32_e32 v50, 0x3f317217, v48
	v_cmp_lt_f32_e64 s[8:9], |v48|, s17
	s_nop 1
	v_cndmask_b32_e64 v48, v48, v50, s[8:9]
	v_cndmask_b32_e64 v50, 0, v213, s[0:1]
	v_sub_f32_e32 v48, v48, v50
	v_cndmask_b32_e64 v47, v48, -v47, vcc
	v_add_f32_e32 v48, v49, v53
	v_mul_f32_e32 v49, 0xbfb8aa3b, v48
	v_exp_f32_e32 v49, v49
	v_cmp_gt_f32_e32 vcc, s15, v48
	v_sub_f32_e32 v47, -0.5, v47
	v_mul_f32_e32 v47, 0x3fb8aa3b, v47
	v_add_f32_e32 v49, 1.0, v49
	v_cmp_gt_f32_e64 s[0:1], s14, v49
	v_exp_f32_e32 v47, v47
	s_nop 0
	v_cndmask_b32_e64 v50, 0, 32, s[0:1]
	v_ldexp_f32 v49, v49, v50
	v_log_f32_e32 v49, v49
	s_nop 0
	v_mul_f32_e32 v50, 0x3f317217, v49
	v_fma_f32 v50, v49, s16, -v50
	v_fmac_f32_e32 v50, 0x3377d1cf, v49
	v_fmac_f32_e32 v50, 0x3f317217, v49
	v_cmp_lt_f32_e64 s[8:9], |v49|, s17
	s_nop 1
	v_cndmask_b32_e64 v49, v49, v50, s[8:9]
	v_cndmask_b32_e64 v50, 0, v213, s[0:1]
	v_sub_f32_e32 v49, v49, v50
	v_cndmask_b32_e64 v48, v49, -v48, vcc
	v_sub_f32_e32 v48, -0.5, v48
	v_mul_f32_e32 v48, 0x3fb8aa3b, v48
	v_exp_f32_e32 v48, v48
	v_mov_b32_e32 v49, v9
	v_cvt_pk_bf16_f32 v47, v47, v48
	v_add_u32_e32 v48, v58, v70
	v_lshl_add_u64 v[48:49], v[48:49], 1, s[12:13]
	global_store_dwordx2 v[48:49], v[46:47], off
	v_mov_b32_e32 v46, v178
	v_mov_b32_e32 v47, v179
	v_mov_b32_e32 v48, v180
	v_mov_b32_e32 v49, v181
	v_add_f32_e32 v42, v42, v46
	v_mul_f32_e32 v46, 0xbfb8aa3b, v42
	v_exp_f32_e32 v46, v46
	v_cmp_gt_f32_e32 vcc, s15, v42
	v_add_f32_e32 v43, v43, v47
	v_add_f32_e32 v46, 1.0, v46
	v_cmp_gt_f32_e64 s[0:1], s14, v46
	s_nop 1
	v_cndmask_b32_e64 v50, 0, 32, s[0:1]
	v_ldexp_f32 v46, v46, v50
	v_log_f32_e32 v46, v46
	s_nop 0
	v_mul_f32_e32 v50, 0x3f317217, v46
	v_fma_f32 v50, v46, s16, -v50
	v_fmac_f32_e32 v50, 0x3377d1cf, v46
	v_fmac_f32_e32 v50, 0x3f317217, v46
	v_cmp_lt_f32_e64 s[8:9], |v46|, s17
	s_nop 1
	v_cndmask_b32_e64 v46, v46, v50, s[8:9]
	v_cndmask_b32_e64 v50, 0, v213, s[0:1]
	v_sub_f32_e32 v46, v46, v50
	v_cndmask_b32_e64 v42, v46, -v42, vcc
; __device__ __forceinline__ float softplusf_(float x) { return x > 20.f ? x : __logf(1.f + __expf(x)); }
;     ...
;             } else if constexpr (EPI == EPI_LW) {
;               const float4 w0v = *(const float4*)(e.v0 + col);
;               uint2 o;
;               o.x = pack2(__expf(-softplusf_(-(w0v.x + a[0])) - 0.5f), __expf(-softplusf_(-(w0v.y + a[1])) - 0.5f));
;               o.y = pack2(__expf(-softplusf_(-(w0v.z + a[2])) - 0.5f), __expf(-softplusf_(-(w0v.w + a[3])) - 0.5f));
;               *(uint2*)(e.b0 + (row * (unsigned)D + col)) = o;
	v_mul_f32_e32 v46, 0xbfb8aa3b, v43
	v_exp_f32_e32 v46, v46
	v_cmp_gt_f32_e32 vcc, s15, v43
	v_sub_f32_e32 v42, -0.5, v42
	v_mul_f32_e32 v42, 0x3fb8aa3b, v42
	v_add_f32_e32 v46, 1.0, v46
	v_cmp_gt_f32_e64 s[0:1], s14, v46
	v_exp_f32_e32 v42, v42
	s_nop 0
	v_cndmask_b32_e64 v47, 0, 32, s[0:1]
	v_ldexp_f32 v46, v46, v47
	v_log_f32_e32 v46, v46
	s_nop 0
	v_mul_f32_e32 v47, 0x3f317217, v46
	v_fma_f32 v47, v46, s16, -v47
	v_fmac_f32_e32 v47, 0x3377d1cf, v46
	v_fmac_f32_e32 v47, 0x3f317217, v46
	v_cmp_lt_f32_e64 s[8:9], |v46|, s17
	s_nop 1
	v_cndmask_b32_e64 v46, v46, v47, s[8:9]
	v_cndmask_b32_e64 v47, 0, v213, s[0:1]
	v_sub_f32_e32 v46, v46, v47
	v_cndmask_b32_e64 v43, v46, -v43, vcc
	v_sub_f32_e32 v43, -0.5, v43
	v_mul_f32_e32 v43, 0x3fb8aa3b, v43
	v_exp_f32_e32 v43, v43
	s_nop 0
	v_cvt_pk_bf16_f32 v42, v42, v43
	v_add_f32_e32 v43, v44, v48
	v_mul_f32_e32 v44, 0xbfb8aa3b, v43
	v_exp_f32_e32 v44, v44
	v_cmp_gt_f32_e32 vcc, s15, v43
	v_add_f32_e32 v44, 1.0, v44
	v_cmp_gt_f32_e64 s[0:1], s14, v44
	s_nop 1
	v_cndmask_b32_e64 v46, 0, 32, s[0:1]
	v_ldexp_f32 v44, v44, v46
	v_log_f32_e32 v44, v44
	s_nop 0
	v_mul_f32_e32 v46, 0x3f317217, v44
	v_fma_f32 v46, v44, s16, -v46
	v_fmac_f32_e32 v46, 0x3377d1cf, v44
	v_fmac_f32_e32 v46, 0x3f317217, v44
	v_cmp_lt_f32_e64 s[8:9], |v44|, s17
	s_nop 1
	v_cndmask_b32_e64 v44, v44, v46, s[8:9]
	v_cndmask_b32_e64 v46, 0, v213, s[0:1]
	v_sub_f32_e32 v44, v44, v46
	v_cndmask_b32_e64 v43, v44, -v43, vcc
	v_add_f32_e32 v44, v45, v49
	v_mul_f32_e32 v45, 0xbfb8aa3b, v44
	v_exp_f32_e32 v45, v45
	v_cmp_gt_f32_e32 vcc, s15, v44
	v_sub_f32_e32 v43, -0.5, v43
	v_mul_f32_e32 v43, 0x3fb8aa3b, v43
	v_add_f32_e32 v45, 1.0, v45
	v_cmp_gt_f32_e64 s[0:1], s14, v45
	v_exp_f32_e32 v43, v43
	s_nop 0
	v_cndmask_b32_e64 v46, 0, 32, s[0:1]
	v_ldexp_f32 v45, v45, v46
	v_log_f32_e32 v45, v45
	s_nop 0
	v_mul_f32_e32 v46, 0x3f317217, v45
	v_fma_f32 v46, v45, s16, -v46
	v_fmac_f32_e32 v46, 0x3377d1cf, v45
	v_fmac_f32_e32 v46, 0x3f317217, v45
	v_cmp_lt_f32_e64 s[8:9], |v45|, s17
	s_nop 1
	v_cndmask_b32_e64 v45, v45, v46, s[8:9]
	v_cndmask_b32_e64 v46, 0, v213, s[0:1]
	v_sub_f32_e32 v45, v45, v46
	v_cndmask_b32_e64 v44, v45, -v44, vcc
	v_sub_f32_e32 v44, -0.5, v44
	v_mul_f32_e32 v44, 0x3fb8aa3b, v44
	v_exp_f32_e32 v44, v44
	v_mov_b32_e32 v45, v9
	v_cvt_pk_bf16_f32 v43, v43, v44
	v_add_u32_e32 v44, v58, v66
	v_lshl_add_u64 v[44:45], v[44:45], 1, s[12:13]
	global_store_dwordx2 v[44:45], v[42:43], off
	v_or_b32_e32 v42, 0x8000, v88
	v_mov_b32_e32 v44, v166
	v_mov_b32_e32 v45, v167
	v_mov_b32_e32 v46, v168
	v_mov_b32_e32 v47, v169
	v_add_f32_e32 v38, v38, v44
	v_mul_f32_e32 v43, 0xbfb8aa3b, v38
	v_exp_f32_e32 v43, v43
	v_cmp_gt_f32_e32 vcc, s15, v38
	v_add_f32_e32 v39, v39, v45
	v_add_f32_e32 v43, 1.0, v43
	v_cmp_gt_f32_e64 s[0:1], s14, v43
	s_nop 1
	v_cndmask_b32_e64 v44, 0, 32, s[0:1]
	v_ldexp_f32 v43, v43, v44
	v_log_f32_e32 v43, v43
	s_nop 0
	v_mul_f32_e32 v44, 0x3f317217, v43
	v_fma_f32 v44, v43, s16, -v44
	v_fmac_f32_e32 v44, 0x3377d1cf, v43
	v_fmac_f32_e32 v44, 0x3f317217, v43
	v_cmp_lt_f32_e64 s[8:9], |v43|, s17
	s_nop 1
	v_cndmask_b32_e64 v43, v43, v44, s[8:9]
	v_cndmask_b32_e64 v44, 0, v213, s[0:1]
	v_sub_f32_e32 v43, v43, v44
	v_cndmask_b32_e64 v38, v43, -v38, vcc
	v_mul_f32_e32 v43, 0xbfb8aa3b, v39
	v_exp_f32_e32 v43, v43
	v_cmp_gt_f32_e32 vcc, s15, v39
	v_sub_f32_e32 v38, -0.5, v38
	v_mul_f32_e32 v38, 0x3fb8aa3b, v38
	v_add_f32_e32 v43, 1.0, v43
	v_cmp_gt_f32_e64 s[0:1], s14, v43
	v_exp_f32_e32 v38, v38
	s_nop 0
	v_cndmask_b32_e64 v44, 0, 32, s[0:1]
	v_ldexp_f32 v43, v43, v44
	v_log_f32_e32 v43, v43
	s_nop 0
	v_mul_f32_e32 v44, 0x3f317217, v43
	v_fma_f32 v44, v43, s16, -v44
	v_fmac_f32_e32 v44, 0x3377d1cf, v43
	v_fmac_f32_e32 v44, 0x3f317217, v43
	v_cmp_lt_f32_e64 s[8:9], |v43|, s17
	s_nop 1
	v_cndmask_b32_e64 v43, v43, v44, s[8:9]
	v_cndmask_b32_e64 v44, 0, v213, s[0:1]
	v_sub_f32_e32 v43, v43, v44
	v_cndmask_b32_e64 v39, v43, -v39, vcc
	v_sub_f32_e32 v39, -0.5, v39
	v_mul_f32_e32 v39, 0x3fb8aa3b, v39
	v_exp_f32_e32 v39, v39
	s_nop 0
	v_cvt_pk_bf16_f32 v38, v38, v39
	v_add_f32_e32 v39, v40, v46
	v_mul_f32_e32 v40, 0xbfb8aa3b, v39
	v_exp_f32_e32 v40, v40
	v_cmp_gt_f32_e32 vcc, s15, v39
	v_add_f32_e32 v40, 1.0, v40
	v_cmp_gt_f32_e64 s[0:1], s14, v40
	s_nop 1
	v_cndmask_b32_e64 v43, 0, 32, s[0:1]
	v_ldexp_f32 v40, v40, v43
	v_log_f32_e32 v40, v40
	s_nop 0
	v_mul_f32_e32 v43, 0x3f317217, v40
	v_fma_f32 v43, v40, s16, -v43
	v_fmac_f32_e32 v43, 0x3377d1cf, v40
	v_fmac_f32_e32 v43, 0x3f317217, v40
	v_cmp_lt_f32_e64 s[8:9], |v40|, s17
	s_nop 1
	v_cndmask_b32_e64 v40, v40, v43, s[8:9]
	v_cndmask_b32_e64 v43, 0, v213, s[0:1]
	v_sub_f32_e32 v40, v40, v43
	v_cndmask_b32_e64 v39, v40, -v39, vcc
	v_add_f32_e32 v40, v41, v47
	v_mul_f32_e32 v41, 0xbfb8aa3b, v40
	v_exp_f32_e32 v41, v41
	v_cmp_gt_f32_e32 vcc, s15, v40
	v_sub_f32_e32 v39, -0.5, v39
	v_mul_f32_e32 v39, 0x3fb8aa3b, v39
	v_add_f32_e32 v41, 1.0, v41
	v_cmp_gt_f32_e64 s[0:1], s14, v41
	v_exp_f32_e32 v39, v39
	s_nop 0
	v_cndmask_b32_e64 v43, 0, 32, s[0:1]
	v_ldexp_f32 v41, v41, v43
	v_log_f32_e32 v41, v41
	s_nop 0
	v_mul_f32_e32 v43, 0x3f317217, v41
	v_fma_f32 v43, v41, s16, -v43
	v_fmac_f32_e32 v43, 0x3377d1cf, v41
	v_fmac_f32_e32 v43, 0x3f317217, v41
	v_cmp_lt_f32_e64 s[8:9], |v41|, s17
	s_nop 1
	v_cndmask_b32_e64 v41, v41, v43, s[8:9]
	v_cndmask_b32_e64 v43, 0, v213, s[0:1]
	v_sub_f32_e32 v41, v41, v43
	v_cndmask_b32_e64 v40, v41, -v40, vcc
	v_sub_f32_e32 v40, -0.5, v40
	v_mul_f32_e32 v40, 0x3fb8aa3b, v40
	v_exp_f32_e32 v40, v40
	v_mov_b32_e32 v41, v9
	v_cvt_pk_bf16_f32 v39, v39, v40
	v_add_u32_e32 v40, v42, v8
	v_lshl_add_u64 v[40:41], v[40:41], 1, s[12:13]
	global_store_dwordx2 v[40:41], v[38:39], off
; __device__ __forceinline__ float softplusf_(float x) { return x > 20.f ? x : __logf(1.f + __expf(x)); }
;     ...
;             } else if constexpr (EPI == EPI_LW) {
;               const float4 w0v = *(const float4*)(e.v0 + col);
;               uint2 o;
;               o.x = pack2(__expf(-softplusf_(-(w0v.x + a[0])) - 0.5f), __expf(-softplusf_(-(w0v.y + a[1])) - 0.5f));
;               o.y = pack2(__expf(-softplusf_(-(w0v.z + a[2])) - 0.5f), __expf(-softplusf_(-(w0v.w + a[3])) - 0.5f));
;               *(uint2*)(e.b0 + (row * (unsigned)D + col)) = o;
	v_mov_b32_e32 v38, v170
	v_mov_b32_e32 v39, v171
	v_mov_b32_e32 v40, v172
	v_mov_b32_e32 v41, v173
	v_add_f32_e32 v34, v34, v38
	v_mul_f32_e32 v38, 0xbfb8aa3b, v34
	v_exp_f32_e32 v38, v38
	v_cmp_gt_f32_e32 vcc, s15, v34
	v_add_f32_e32 v35, v35, v39
	v_add_f32_e32 v38, 1.0, v38
	v_cmp_gt_f32_e64 s[0:1], s14, v38
	s_nop 1
	v_cndmask_b32_e64 v43, 0, 32, s[0:1]
	v_ldexp_f32 v38, v38, v43
	v_log_f32_e32 v38, v38
	s_nop 0
	v_mul_f32_e32 v43, 0x3f317217, v38
	v_fma_f32 v43, v38, s16, -v43
	v_fmac_f32_e32 v43, 0x3377d1cf, v38
	v_fmac_f32_e32 v43, 0x3f317217, v38
	v_cmp_lt_f32_e64 s[8:9], |v38|, s17
	s_nop 1
	v_cndmask_b32_e64 v38, v38, v43, s[8:9]
	v_cndmask_b32_e64 v43, 0, v213, s[0:1]
	v_sub_f32_e32 v38, v38, v43
	v_cndmask_b32_e64 v34, v38, -v34, vcc
	v_mul_f32_e32 v38, 0xbfb8aa3b, v35
	v_exp_f32_e32 v38, v38
	v_cmp_gt_f32_e32 vcc, s15, v35
	v_sub_f32_e32 v34, -0.5, v34
	v_mul_f32_e32 v34, 0x3fb8aa3b, v34
	v_add_f32_e32 v38, 1.0, v38
	v_cmp_gt_f32_e64 s[0:1], s14, v38
	v_exp_f32_e32 v34, v34
	s_nop 0
	v_cndmask_b32_e64 v39, 0, 32, s[0:1]
	v_ldexp_f32 v38, v38, v39
	v_log_f32_e32 v38, v38
	s_nop 0
	v_mul_f32_e32 v39, 0x3f317217, v38
	v_fma_f32 v39, v38, s16, -v39
	v_fmac_f32_e32 v39, 0x3377d1cf, v38
	v_fmac_f32_e32 v39, 0x3f317217, v38
	v_cmp_lt_f32_e64 s[8:9], |v38|, s17
	s_nop 1
	v_cndmask_b32_e64 v38, v38, v39, s[8:9]
	v_cndmask_b32_e64 v39, 0, v213, s[0:1]
	v_sub_f32_e32 v38, v38, v39
	v_cndmask_b32_e64 v35, v38, -v35, vcc
	v_sub_f32_e32 v35, -0.5, v35
	v_mul_f32_e32 v35, 0x3fb8aa3b, v35
	v_exp_f32_e32 v35, v35
	s_nop 0
	v_cvt_pk_bf16_f32 v34, v34, v35
	v_add_f32_e32 v35, v36, v40
	v_mul_f32_e32 v36, 0xbfb8aa3b, v35
	v_exp_f32_e32 v36, v36
	v_cmp_gt_f32_e32 vcc, s15, v35
	v_add_f32_e32 v36, 1.0, v36
	v_cmp_gt_f32_e64 s[0:1], s14, v36
	s_nop 1
	v_cndmask_b32_e64 v38, 0, 32, s[0:1]
	v_ldexp_f32 v36, v36, v38
	v_log_f32_e32 v36, v36
	s_nop 0
	v_mul_f32_e32 v38, 0x3f317217, v36
	v_fma_f32 v38, v36, s16, -v38
	v_fmac_f32_e32 v38, 0x3377d1cf, v36
	v_fmac_f32_e32 v38, 0x3f317217, v36
	v_cmp_lt_f32_e64 s[8:9], |v36|, s17
	s_nop 1
	v_cndmask_b32_e64 v36, v36, v38, s[8:9]
	v_cndmask_b32_e64 v38, 0, v213, s[0:1]
	v_sub_f32_e32 v36, v36, v38
	v_cndmask_b32_e64 v35, v36, -v35, vcc
	v_add_f32_e32 v36, v37, v41
	v_mul_f32_e32 v37, 0xbfb8aa3b, v36
	v_exp_f32_e32 v37, v37
	v_cmp_gt_f32_e32 vcc, s15, v36
	v_sub_f32_e32 v35, -0.5, v35
	v_mul_f32_e32 v35, 0x3fb8aa3b, v35
	v_add_f32_e32 v37, 1.0, v37
	v_cmp_gt_f32_e64 s[0:1], s14, v37
	v_exp_f32_e32 v35, v35
	s_nop 0
	v_cndmask_b32_e64 v38, 0, 32, s[0:1]
	v_ldexp_f32 v37, v37, v38
	v_log_f32_e32 v37, v37
	s_nop 0
	v_mul_f32_e32 v38, 0x3f317217, v37
	v_fma_f32 v38, v37, s16, -v38
	v_fmac_f32_e32 v38, 0x3377d1cf, v37
	v_fmac_f32_e32 v38, 0x3f317217, v37
	v_cmp_lt_f32_e64 s[8:9], |v37|, s17
	s_nop 1
	v_cndmask_b32_e64 v37, v37, v38, s[8:9]
	v_cndmask_b32_e64 v38, 0, v213, s[0:1]
	v_sub_f32_e32 v37, v37, v38
	v_cndmask_b32_e64 v36, v37, -v36, vcc
	v_sub_f32_e32 v36, -0.5, v36
	v_mul_f32_e32 v36, 0x3fb8aa3b, v36
	v_exp_f32_e32 v36, v36
	v_mov_b32_e32 v37, v9
	v_cvt_pk_bf16_f32 v35, v35, v36
	v_add_u32_e32 v36, v42, v71
	v_lshl_add_u64 v[36:37], v[36:37], 1, s[12:13]
	global_store_dwordx2 v[36:37], v[34:35], off
	v_mov_b32_e32 v34, v174
	v_mov_b32_e32 v35, v175
	v_mov_b32_e32 v36, v176
	v_mov_b32_e32 v37, v177
	v_add_f32_e32 v30, v30, v34
	v_mul_f32_e32 v34, 0xbfb8aa3b, v30
	v_exp_f32_e32 v34, v34
	v_cmp_gt_f32_e32 vcc, s15, v30
	v_add_f32_e32 v31, v31, v35
	v_add_f32_e32 v34, 1.0, v34
	v_cmp_gt_f32_e64 s[0:1], s14, v34
	s_nop 1
	v_cndmask_b32_e64 v38, 0, 32, s[0:1]
	v_ldexp_f32 v34, v34, v38
	v_log_f32_e32 v34, v34
	s_nop 0
	v_mul_f32_e32 v38, 0x3f317217, v34
	v_fma_f32 v38, v34, s16, -v38
	v_fmac_f32_e32 v38, 0x3377d1cf, v34
	v_fmac_f32_e32 v38, 0x3f317217, v34
	v_cmp_lt_f32_e64 s[8:9], |v34|, s17
	s_nop 1
	v_cndmask_b32_e64 v34, v34, v38, s[8:9]
	v_cndmask_b32_e64 v38, 0, v213, s[0:1]
	v_sub_f32_e32 v34, v34, v38
	v_cndmask_b32_e64 v30, v34, -v30, vcc
	v_mul_f32_e32 v34, 0xbfb8aa3b, v31
	v_exp_f32_e32 v34, v34
	v_cmp_gt_f32_e32 vcc, s15, v31
	v_sub_f32_e32 v30, -0.5, v30
	v_mul_f32_e32 v30, 0x3fb8aa3b, v30
	v_add_f32_e32 v34, 1.0, v34
	v_cmp_gt_f32_e64 s[0:1], s14, v34
	v_exp_f32_e32 v30, v30
	s_nop 0
	v_cndmask_b32_e64 v35, 0, 32, s[0:1]
	v_ldexp_f32 v34, v34, v35
	v_log_f32_e32 v34, v34
	s_nop 0
	v_mul_f32_e32 v35, 0x3f317217, v34
	v_fma_f32 v35, v34, s16, -v35
	v_fmac_f32_e32 v35, 0x3377d1cf, v34
	v_fmac_f32_e32 v35, 0x3f317217, v34
	v_cmp_lt_f32_e64 s[8:9], |v34|, s17
	s_nop 1
	v_cndmask_b32_e64 v34, v34, v35, s[8:9]
	v_cndmask_b32_e64 v35, 0, v213, s[0:1]
	v_sub_f32_e32 v34, v34, v35
	v_cndmask_b32_e64 v31, v34, -v31, vcc
	v_sub_f32_e32 v31, -0.5, v31
	v_mul_f32_e32 v31, 0x3fb8aa3b, v31
	v_exp_f32_e32 v31, v31
	s_nop 0
	v_cvt_pk_bf16_f32 v30, v30, v31
	v_add_f32_e32 v31, v32, v36
	v_mul_f32_e32 v32, 0xbfb8aa3b, v31
	v_exp_f32_e32 v32, v32
	v_cmp_gt_f32_e32 vcc, s15, v31
	v_add_f32_e32 v32, 1.0, v32
	v_cmp_gt_f32_e64 s[0:1], s14, v32
	s_nop 1
	v_cndmask_b32_e64 v34, 0, 32, s[0:1]
	v_ldexp_f32 v32, v32, v34
	v_log_f32_e32 v32, v32
	s_nop 0
	v_mul_f32_e32 v34, 0x3f317217, v32
	v_fma_f32 v34, v32, s16, -v34
	v_fmac_f32_e32 v34, 0x3377d1cf, v32
	v_fmac_f32_e32 v34, 0x3f317217, v32
	v_cmp_lt_f32_e64 s[8:9], |v32|, s17
	s_nop 1
	v_cndmask_b32_e64 v32, v32, v34, s[8:9]
	v_cndmask_b32_e64 v34, 0, v213, s[0:1]
	v_sub_f32_e32 v32, v32, v34
	v_cndmask_b32_e64 v31, v32, -v31, vcc
	v_add_f32_e32 v32, v33, v37
	v_mul_f32_e32 v33, 0xbfb8aa3b, v32
	v_exp_f32_e32 v33, v33
	v_cmp_gt_f32_e32 vcc, s15, v32
	v_sub_f32_e32 v31, -0.5, v31
	v_mul_f32_e32 v31, 0x3fb8aa3b, v31
	v_add_f32_e32 v33, 1.0, v33
	v_cmp_gt_f32_e64 s[0:1], s14, v33
; __device__ __forceinline__ float softplusf_(float x) { return x > 20.f ? x : __logf(1.f + __expf(x)); }
;     ...
;             } else if constexpr (EPI == EPI_LW) {
;               const float4 w0v = *(const float4*)(e.v0 + col);
;               uint2 o;
;               o.x = pack2(__expf(-softplusf_(-(w0v.x + a[0])) - 0.5f), __expf(-softplusf_(-(w0v.y + a[1])) - 0.5f));
;               o.y = pack2(__expf(-softplusf_(-(w0v.z + a[2])) - 0.5f), __expf(-softplusf_(-(w0v.w + a[3])) - 0.5f));
;               *(uint2*)(e.b0 + (row * (unsigned)D + col)) = o;
	v_exp_f32_e32 v31, v31
	s_nop 0
	v_cndmask_b32_e64 v34, 0, 32, s[0:1]
	v_ldexp_f32 v33, v33, v34
	v_log_f32_e32 v33, v33
	s_nop 0
	v_mul_f32_e32 v34, 0x3f317217, v33
	v_fma_f32 v34, v33, s16, -v34
	v_fmac_f32_e32 v34, 0x3377d1cf, v33
	v_fmac_f32_e32 v34, 0x3f317217, v33
	v_cmp_lt_f32_e64 s[8:9], |v33|, s17
	s_nop 1
	v_cndmask_b32_e64 v33, v33, v34, s[8:9]
	v_cndmask_b32_e64 v34, 0, v213, s[0:1]
	v_sub_f32_e32 v33, v33, v34
	v_cndmask_b32_e64 v32, v33, -v32, vcc
	v_sub_f32_e32 v32, -0.5, v32
	v_mul_f32_e32 v32, 0x3fb8aa3b, v32
	v_exp_f32_e32 v32, v32
	v_mov_b32_e32 v33, v9
	v_cvt_pk_bf16_f32 v31, v31, v32
	v_add_u32_e32 v32, v42, v70
	v_lshl_add_u64 v[32:33], v[32:33], 1, s[12:13]
	global_store_dwordx2 v[32:33], v[30:31], off
	v_mov_b32_e32 v30, v178
	v_mov_b32_e32 v31, v179
	v_mov_b32_e32 v32, v180
	v_mov_b32_e32 v33, v181
	v_add_f32_e32 v26, v26, v30
	v_mul_f32_e32 v30, 0xbfb8aa3b, v26
	v_exp_f32_e32 v30, v30
	v_cmp_gt_f32_e32 vcc, s15, v26
	v_add_f32_e32 v27, v27, v31
	v_add_f32_e32 v30, 1.0, v30
	v_cmp_gt_f32_e64 s[0:1], s14, v30
	s_nop 1
	v_cndmask_b32_e64 v34, 0, 32, s[0:1]
	v_ldexp_f32 v30, v30, v34
	v_log_f32_e32 v30, v30
	s_nop 0
	v_mul_f32_e32 v34, 0x3f317217, v30
	v_fma_f32 v34, v30, s16, -v34
	v_fmac_f32_e32 v34, 0x3377d1cf, v30
	v_fmac_f32_e32 v34, 0x3f317217, v30
	v_cmp_lt_f32_e64 s[8:9], |v30|, s17
	s_nop 1
	v_cndmask_b32_e64 v30, v30, v34, s[8:9]
	v_cndmask_b32_e64 v34, 0, v213, s[0:1]
	v_sub_f32_e32 v30, v30, v34
	v_cndmask_b32_e64 v26, v30, -v26, vcc
	v_mul_f32_e32 v30, 0xbfb8aa3b, v27
	v_exp_f32_e32 v30, v30
	v_cmp_gt_f32_e32 vcc, s15, v27
	v_sub_f32_e32 v26, -0.5, v26
	v_mul_f32_e32 v26, 0x3fb8aa3b, v26
	v_add_f32_e32 v30, 1.0, v30
	v_cmp_gt_f32_e64 s[0:1], s14, v30
	v_exp_f32_e32 v26, v26
	s_nop 0
	v_cndmask_b32_e64 v31, 0, 32, s[0:1]
	v_ldexp_f32 v30, v30, v31
	v_log_f32_e32 v30, v30
	s_nop 0
	v_mul_f32_e32 v31, 0x3f317217, v30
	v_fma_f32 v31, v30, s16, -v31
	v_fmac_f32_e32 v31, 0x3377d1cf, v30
	v_fmac_f32_e32 v31, 0x3f317217, v30
	v_cmp_lt_f32_e64 s[8:9], |v30|, s17
	s_nop 1
	v_cndmask_b32_e64 v30, v30, v31, s[8:9]
	v_cndmask_b32_e64 v31, 0, v213, s[0:1]
	v_sub_f32_e32 v30, v30, v31
	v_cndmask_b32_e64 v27, v30, -v27, vcc
	v_sub_f32_e32 v27, -0.5, v27
	v_mul_f32_e32 v27, 0x3fb8aa3b, v27
	v_exp_f32_e32 v27, v27
	s_nop 0
	v_cvt_pk_bf16_f32 v26, v26, v27
	v_add_f32_e32 v27, v28, v32
	v_mul_f32_e32 v28, 0xbfb8aa3b, v27
	v_exp_f32_e32 v28, v28
	v_cmp_gt_f32_e32 vcc, s15, v27
	v_add_f32_e32 v28, 1.0, v28
	v_cmp_gt_f32_e64 s[0:1], s14, v28
	s_nop 1
	v_cndmask_b32_e64 v30, 0, 32, s[0:1]
	v_ldexp_f32 v28, v28, v30
	v_log_f32_e32 v28, v28
	s_nop 0
	v_mul_f32_e32 v30, 0x3f317217, v28
	v_fma_f32 v30, v28, s16, -v30
	v_fmac_f32_e32 v30, 0x3377d1cf, v28
	v_fmac_f32_e32 v30, 0x3f317217, v28
	v_cmp_lt_f32_e64 s[8:9], |v28|, s17
	s_nop 1
	v_cndmask_b32_e64 v28, v28, v30, s[8:9]
	v_cndmask_b32_e64 v30, 0, v213, s[0:1]
	v_sub_f32_e32 v28, v28, v30
	v_cndmask_b32_e64 v27, v28, -v27, vcc
	v_add_f32_e32 v28, v29, v33
	v_mul_f32_e32 v29, 0xbfb8aa3b, v28
	v_exp_f32_e32 v29, v29
	v_cmp_gt_f32_e32 vcc, s15, v28
	v_sub_f32_e32 v27, -0.5, v27
	v_mul_f32_e32 v27, 0x3fb8aa3b, v27
	v_add_f32_e32 v29, 1.0, v29
	v_cmp_gt_f32_e64 s[0:1], s14, v29
	v_exp_f32_e32 v27, v27
	s_nop 0
	v_cndmask_b32_e64 v30, 0, 32, s[0:1]
	v_ldexp_f32 v29, v29, v30
	v_log_f32_e32 v29, v29
	s_nop 0
	v_mul_f32_e32 v30, 0x3f317217, v29
	v_fma_f32 v30, v29, s16, -v30
	v_fmac_f32_e32 v30, 0x3377d1cf, v29
	v_fmac_f32_e32 v30, 0x3f317217, v29
	v_cmp_lt_f32_e64 s[8:9], |v29|, s17
	s_nop 1
	v_cndmask_b32_e64 v29, v29, v30, s[8:9]
	v_cndmask_b32_e64 v30, 0, v213, s[0:1]
	v_sub_f32_e32 v29, v29, v30
	v_cndmask_b32_e64 v28, v29, -v28, vcc
	v_sub_f32_e32 v28, -0.5, v28
	v_mul_f32_e32 v28, 0x3fb8aa3b, v28
	v_exp_f32_e32 v28, v28
	v_mov_b32_e32 v29, v9
	v_cvt_pk_bf16_f32 v27, v27, v28
	v_add_u32_e32 v28, v42, v66
	v_lshl_add_u64 v[28:29], v[28:29], 1, s[12:13]
	global_store_dwordx2 v[28:29], v[26:27], off
	v_or_b32_e32 v30, 0xc000, v88
	v_add_u32_e32 v8, v30, v8
	v_mov_b32_e32 v26, v166
	v_mov_b32_e32 v27, v167
	v_mov_b32_e32 v28, v168
	v_mov_b32_e32 v29, v169
	v_add_f32_e32 v22, v22, v26
	v_mul_f32_e32 v26, 0xbfb8aa3b, v22
	v_exp_f32_e32 v26, v26
	v_cmp_gt_f32_e32 vcc, s15, v22
	v_add_f32_e32 v23, v23, v27
	v_add_f32_e32 v26, 1.0, v26
	v_cmp_gt_f32_e64 s[0:1], s14, v26
	s_nop 1
	v_cndmask_b32_e64 v31, 0, 32, s[0:1]
	v_ldexp_f32 v26, v26, v31
	v_log_f32_e32 v26, v26
	s_nop 0
	v_mul_f32_e32 v31, 0x3f317217, v26
	v_fma_f32 v31, v26, s16, -v31
	v_fmac_f32_e32 v31, 0x3377d1cf, v26
	v_fmac_f32_e32 v31, 0x3f317217, v26
	v_cmp_lt_f32_e64 s[8:9], |v26|, s17
	s_nop 1
	v_cndmask_b32_e64 v26, v26, v31, s[8:9]
	v_cndmask_b32_e64 v31, 0, v213, s[0:1]
	v_sub_f32_e32 v26, v26, v31
	v_cndmask_b32_e64 v22, v26, -v22, vcc
	v_mul_f32_e32 v26, 0xbfb8aa3b, v23
	v_exp_f32_e32 v26, v26
	v_cmp_gt_f32_e32 vcc, s15, v23
	v_sub_f32_e32 v22, -0.5, v22
	v_mul_f32_e32 v22, 0x3fb8aa3b, v22
	v_add_f32_e32 v26, 1.0, v26
	v_cmp_gt_f32_e64 s[0:1], s14, v26
	v_exp_f32_e32 v22, v22
	s_nop 0
	v_cndmask_b32_e64 v27, 0, 32, s[0:1]
	v_ldexp_f32 v26, v26, v27
	v_log_f32_e32 v26, v26
	s_nop 0
	v_mul_f32_e32 v27, 0x3f317217, v26
	v_fma_f32 v27, v26, s16, -v27
	v_fmac_f32_e32 v27, 0x3377d1cf, v26
	v_fmac_f32_e32 v27, 0x3f317217, v26
	v_cmp_lt_f32_e64 s[8:9], |v26|, s17
	s_nop 1
	v_cndmask_b32_e64 v26, v26, v27, s[8:9]
	v_cndmask_b32_e64 v27, 0, v213, s[0:1]
	v_sub_f32_e32 v26, v26, v27
	v_cndmask_b32_e64 v23, v26, -v23, vcc
	v_sub_f32_e32 v23, -0.5, v23
	v_mul_f32_e32 v23, 0x3fb8aa3b, v23
	v_exp_f32_e32 v23, v23
	s_nop 0
	v_cvt_pk_bf16_f32 v22, v22, v23
	v_add_f32_e32 v23, v24, v28
	v_mul_f32_e32 v24, 0xbfb8aa3b, v23
; __device__ __forceinline__ float softplusf_(float x) { return x > 20.f ? x : __logf(1.f + __expf(x)); }
;     ...
;             } else if constexpr (EPI == EPI_LW) {
;               const float4 w0v = *(const float4*)(e.v0 + col);
;               uint2 o;
;               o.x = pack2(__expf(-softplusf_(-(w0v.x + a[0])) - 0.5f), __expf(-softplusf_(-(w0v.y + a[1])) - 0.5f));
;               o.y = pack2(__expf(-softplusf_(-(w0v.z + a[2])) - 0.5f), __expf(-softplusf_(-(w0v.w + a[3])) - 0.5f));
;               *(uint2*)(e.b0 + (row * (unsigned)D + col)) = o;
	v_exp_f32_e32 v24, v24
	v_cmp_gt_f32_e32 vcc, s15, v23
	v_add_f32_e32 v24, 1.0, v24
	v_cmp_gt_f32_e64 s[0:1], s14, v24
	s_nop 1
	v_cndmask_b32_e64 v26, 0, 32, s[0:1]
	v_ldexp_f32 v24, v24, v26
	v_log_f32_e32 v24, v24
	s_nop 0
	v_mul_f32_e32 v26, 0x3f317217, v24
	v_fma_f32 v26, v24, s16, -v26
	v_fmac_f32_e32 v26, 0x3377d1cf, v24
	v_fmac_f32_e32 v26, 0x3f317217, v24
	v_cmp_lt_f32_e64 s[8:9], |v24|, s17
	s_nop 1
	v_cndmask_b32_e64 v24, v24, v26, s[8:9]
	v_cndmask_b32_e64 v26, 0, v213, s[0:1]
	v_sub_f32_e32 v24, v24, v26
	v_cndmask_b32_e64 v23, v24, -v23, vcc
	v_add_f32_e32 v24, v25, v29
	v_mul_f32_e32 v25, 0xbfb8aa3b, v24
	v_exp_f32_e32 v25, v25
	v_cmp_gt_f32_e32 vcc, s15, v24
	v_sub_f32_e32 v23, -0.5, v23
	v_mul_f32_e32 v23, 0x3fb8aa3b, v23
	v_add_f32_e32 v25, 1.0, v25
	v_cmp_gt_f32_e64 s[0:1], s14, v25
	v_exp_f32_e32 v23, v23
	s_nop 0
	v_cndmask_b32_e64 v26, 0, 32, s[0:1]
	v_ldexp_f32 v25, v25, v26
	v_log_f32_e32 v25, v25
	s_nop 0
	v_mul_f32_e32 v26, 0x3f317217, v25
	v_fma_f32 v26, v25, s16, -v26
	v_fmac_f32_e32 v26, 0x3377d1cf, v25
	v_fmac_f32_e32 v26, 0x3f317217, v25
	v_cmp_lt_f32_e64 s[8:9], |v25|, s17
	s_nop 1
	v_cndmask_b32_e64 v25, v25, v26, s[8:9]
	v_cndmask_b32_e64 v26, 0, v213, s[0:1]
	v_sub_f32_e32 v25, v25, v26
	v_cndmask_b32_e64 v24, v25, -v24, vcc
	v_sub_f32_e32 v24, -0.5, v24
	v_mul_f32_e32 v24, 0x3fb8aa3b, v24
	v_exp_f32_e32 v24, v24
	s_nop 0
	v_cvt_pk_bf16_f32 v23, v23, v24
	v_lshl_add_u64 v[24:25], v[8:9], 1, s[12:13]
	global_store_dwordx2 v[24:25], v[22:23], off
	v_mov_b32_e32 v22, v170
	v_mov_b32_e32 v23, v171
	v_mov_b32_e32 v24, v172
	v_mov_b32_e32 v25, v173
	v_add_f32_e32 v8, v18, v22
	v_mul_f32_e32 v18, 0xbfb8aa3b, v8
	v_exp_f32_e32 v18, v18
	v_cmp_gt_f32_e32 vcc, s15, v8
	v_add_f32_e32 v18, 1.0, v18
	v_cmp_gt_f32_e64 s[0:1], s14, v18
	s_nop 1
	v_cndmask_b32_e64 v22, 0, 32, s[0:1]
	v_ldexp_f32 v18, v18, v22
	v_log_f32_e32 v18, v18
	s_nop 0
	v_mul_f32_e32 v22, 0x3f317217, v18
	v_fma_f32 v22, v18, s16, -v22
	v_fmac_f32_e32 v22, 0x3377d1cf, v18
	v_fmac_f32_e32 v22, 0x3f317217, v18
	v_cmp_lt_f32_e64 s[8:9], |v18|, s17
	s_nop 1
	v_cndmask_b32_e64 v18, v18, v22, s[8:9]
	v_cndmask_b32_e64 v22, 0, v213, s[0:1]
	v_sub_f32_e32 v18, v18, v22
	v_cndmask_b32_e64 v8, v18, -v8, vcc
	v_add_f32_e32 v18, v19, v23
	v_mul_f32_e32 v19, 0xbfb8aa3b, v18
	v_exp_f32_e32 v19, v19
	v_cmp_gt_f32_e32 vcc, s15, v18
	v_sub_f32_e32 v8, -0.5, v8
	v_mul_f32_e32 v8, 0x3fb8aa3b, v8
	v_add_f32_e32 v19, 1.0, v19
	v_cmp_gt_f32_e64 s[0:1], s14, v19
	v_exp_f32_e32 v8, v8
	s_nop 0
	v_cndmask_b32_e64 v22, 0, 32, s[0:1]
	v_ldexp_f32 v19, v19, v22
	v_log_f32_e32 v19, v19
	s_nop 0
	v_mul_f32_e32 v22, 0x3f317217, v19
	v_fma_f32 v22, v19, s16, -v22
	v_fmac_f32_e32 v22, 0x3377d1cf, v19
	v_fmac_f32_e32 v22, 0x3f317217, v19
	v_cmp_lt_f32_e64 s[8:9], |v19|, s17
	s_nop 1
	v_cndmask_b32_e64 v19, v19, v22, s[8:9]
	v_cndmask_b32_e64 v22, 0, v213, s[0:1]
	v_sub_f32_e32 v19, v19, v22
	v_cndmask_b32_e64 v18, v19, -v18, vcc
	v_sub_f32_e32 v18, -0.5, v18
	v_mul_f32_e32 v18, 0x3fb8aa3b, v18
	v_exp_f32_e32 v18, v18
	s_nop 0
	v_cvt_pk_bf16_f32 v18, v8, v18
	v_add_f32_e32 v8, v20, v24
	v_mul_f32_e32 v19, 0xbfb8aa3b, v8
	v_exp_f32_e32 v19, v19
	v_cmp_gt_f32_e32 vcc, s15, v8
	v_add_f32_e32 v19, 1.0, v19
	v_cmp_gt_f32_e64 s[0:1], s14, v19
	s_nop 1
	v_cndmask_b32_e64 v20, 0, 32, s[0:1]
	v_ldexp_f32 v19, v19, v20
	v_log_f32_e32 v19, v19
	s_nop 0
	v_mul_f32_e32 v20, 0x3f317217, v19
	v_fma_f32 v20, v19, s16, -v20
	v_fmac_f32_e32 v20, 0x3377d1cf, v19
	v_fmac_f32_e32 v20, 0x3f317217, v19
	v_cmp_lt_f32_e64 s[8:9], |v19|, s17
	s_nop 1
	v_cndmask_b32_e64 v19, v19, v20, s[8:9]
	v_cndmask_b32_e64 v20, 0, v213, s[0:1]
	v_sub_f32_e32 v19, v19, v20
	v_cndmask_b32_e64 v8, v19, -v8, vcc
	v_add_f32_e32 v19, v21, v25
	v_mul_f32_e32 v20, 0xbfb8aa3b, v19
	v_exp_f32_e32 v20, v20
	v_cmp_gt_f32_e32 vcc, s15, v19
	v_sub_f32_e32 v8, -0.5, v8
	v_mul_f32_e32 v8, 0x3fb8aa3b, v8
	v_add_f32_e32 v20, 1.0, v20
	v_cmp_gt_f32_e64 s[0:1], s14, v20
	v_exp_f32_e32 v8, v8
	s_nop 0
	v_cndmask_b32_e64 v21, 0, 32, s[0:1]
	v_ldexp_f32 v20, v20, v21
	v_log_f32_e32 v20, v20
	s_nop 0
	v_mul_f32_e32 v21, 0x3f317217, v20
	v_fma_f32 v21, v20, s16, -v21
	v_fmac_f32_e32 v21, 0x3377d1cf, v20
	v_fmac_f32_e32 v21, 0x3f317217, v20
	v_cmp_lt_f32_e64 s[8:9], |v20|, s17
	s_nop 1
	v_cndmask_b32_e64 v20, v20, v21, s[8:9]
	v_cndmask_b32_e64 v21, 0, v213, s[0:1]
	v_sub_f32_e32 v20, v20, v21
	v_cndmask_b32_e64 v19, v20, -v19, vcc
	v_sub_f32_e32 v19, -0.5, v19
	v_mul_f32_e32 v19, 0x3fb8aa3b, v19
	v_exp_f32_e32 v19, v19
	s_nop 0
	v_cvt_pk_bf16_f32 v19, v8, v19
	v_add_u32_e32 v8, v30, v71
	v_lshl_add_u64 v[20:21], v[8:9], 1, s[12:13]
	global_store_dwordx2 v[20:21], v[18:19], off
	v_mov_b32_e32 v18, v174
	v_mov_b32_e32 v19, v175
	v_mov_b32_e32 v20, v176
	v_mov_b32_e32 v21, v177
	v_add_f32_e32 v8, v14, v18
	v_mul_f32_e32 v14, 0xbfb8aa3b, v8
	v_exp_f32_e32 v14, v14
	v_cmp_gt_f32_e32 vcc, s15, v8
	v_add_f32_e32 v14, 1.0, v14
	v_cmp_gt_f32_e64 s[0:1], s14, v14
	s_nop 1
	v_cndmask_b32_e64 v18, 0, 32, s[0:1]
	v_ldexp_f32 v14, v14, v18
	v_log_f32_e32 v14, v14
	s_nop 0
	v_mul_f32_e32 v18, 0x3f317217, v14
	v_fma_f32 v18, v14, s16, -v18
	v_fmac_f32_e32 v18, 0x3377d1cf, v14
	v_fmac_f32_e32 v18, 0x3f317217, v14
	v_cmp_lt_f32_e64 s[8:9], |v14|, s17
	s_nop 1
	v_cndmask_b32_e64 v14, v14, v18, s[8:9]
	v_cndmask_b32_e64 v18, 0, v213, s[0:1]
	v_sub_f32_e32 v14, v14, v18
	v_cndmask_b32_e64 v8, v14, -v8, vcc
	v_add_f32_e32 v14, v15, v19
	v_mul_f32_e32 v15, 0xbfb8aa3b, v14
	v_exp_f32_e32 v15, v15
	v_cmp_gt_f32_e32 vcc, s15, v14
; __device__ __forceinline__ float softplusf_(float x) { return x > 20.f ? x : __logf(1.f + __expf(x)); }
;     ...
;             } else if constexpr (EPI == EPI_LW) {
;               const float4 w0v = *(const float4*)(e.v0 + col);
;               uint2 o;
;               o.x = pack2(__expf(-softplusf_(-(w0v.x + a[0])) - 0.5f), __expf(-softplusf_(-(w0v.y + a[1])) - 0.5f));
;               o.y = pack2(__expf(-softplusf_(-(w0v.z + a[2])) - 0.5f), __expf(-softplusf_(-(w0v.w + a[3])) - 0.5f));
;               *(uint2*)(e.b0 + (row * (unsigned)D + col)) = o;
	v_sub_f32_e32 v8, -0.5, v8
	v_mul_f32_e32 v8, 0x3fb8aa3b, v8
	v_add_f32_e32 v15, 1.0, v15
	v_cmp_gt_f32_e64 s[0:1], s14, v15
	v_exp_f32_e32 v8, v8
	s_nop 0
	v_cndmask_b32_e64 v18, 0, 32, s[0:1]
	v_ldexp_f32 v15, v15, v18
	v_log_f32_e32 v15, v15
	s_nop 0
	v_mul_f32_e32 v18, 0x3f317217, v15
	v_fma_f32 v18, v15, s16, -v18
	v_fmac_f32_e32 v18, 0x3377d1cf, v15
	v_fmac_f32_e32 v18, 0x3f317217, v15
	v_cmp_lt_f32_e64 s[8:9], |v15|, s17
	s_nop 1
	v_cndmask_b32_e64 v15, v15, v18, s[8:9]
	v_cndmask_b32_e64 v18, 0, v213, s[0:1]
	v_sub_f32_e32 v15, v15, v18
	v_cndmask_b32_e64 v14, v15, -v14, vcc
	v_sub_f32_e32 v14, -0.5, v14
	v_mul_f32_e32 v14, 0x3fb8aa3b, v14
	v_exp_f32_e32 v14, v14
	s_nop 0
	v_cvt_pk_bf16_f32 v14, v8, v14
	v_add_f32_e32 v8, v16, v20
	v_mul_f32_e32 v15, 0xbfb8aa3b, v8
	v_exp_f32_e32 v15, v15
	v_cmp_gt_f32_e32 vcc, s15, v8
	v_add_f32_e32 v15, 1.0, v15
	v_cmp_gt_f32_e64 s[0:1], s14, v15
	s_nop 1
	v_cndmask_b32_e64 v16, 0, 32, s[0:1]
	v_ldexp_f32 v15, v15, v16
	v_log_f32_e32 v15, v15
	s_nop 0
	v_mul_f32_e32 v16, 0x3f317217, v15
	v_fma_f32 v16, v15, s16, -v16
	v_fmac_f32_e32 v16, 0x3377d1cf, v15
	v_fmac_f32_e32 v16, 0x3f317217, v15
	v_cmp_lt_f32_e64 s[8:9], |v15|, s17
	s_nop 1
	v_cndmask_b32_e64 v15, v15, v16, s[8:9]
	v_cndmask_b32_e64 v16, 0, v213, s[0:1]
	v_sub_f32_e32 v15, v15, v16
	v_cndmask_b32_e64 v8, v15, -v8, vcc
	v_add_f32_e32 v15, v17, v21
	v_mul_f32_e32 v16, 0xbfb8aa3b, v15
	v_exp_f32_e32 v16, v16
	v_cmp_gt_f32_e32 vcc, s15, v15
	v_sub_f32_e32 v8, -0.5, v8
	v_mul_f32_e32 v8, 0x3fb8aa3b, v8
	v_add_f32_e32 v16, 1.0, v16
	v_cmp_gt_f32_e64 s[0:1], s14, v16
	v_exp_f32_e32 v8, v8
	s_nop 0
	v_cndmask_b32_e64 v17, 0, 32, s[0:1]
	v_ldexp_f32 v16, v16, v17
	v_log_f32_e32 v16, v16
	s_nop 0
	v_mul_f32_e32 v17, 0x3f317217, v16
	v_fma_f32 v17, v16, s16, -v17
	v_fmac_f32_e32 v17, 0x3377d1cf, v16
	v_fmac_f32_e32 v17, 0x3f317217, v16
	v_cmp_lt_f32_e64 s[8:9], |v16|, s17
	s_nop 1
	v_cndmask_b32_e64 v16, v16, v17, s[8:9]
	v_cndmask_b32_e64 v17, 0, v213, s[0:1]
	v_sub_f32_e32 v16, v16, v17
	v_cndmask_b32_e64 v15, v16, -v15, vcc
	v_sub_f32_e32 v15, -0.5, v15
	v_mul_f32_e32 v15, 0x3fb8aa3b, v15
	v_exp_f32_e32 v15, v15
	s_nop 0
	v_cvt_pk_bf16_f32 v15, v8, v15
	v_add_u32_e32 v8, v30, v70
	v_lshl_add_u64 v[16:17], v[8:9], 1, s[12:13]
	global_store_dwordx2 v[16:17], v[14:15], off
	v_mov_b32_e32 v14, v178
	v_mov_b32_e32 v15, v179
	v_mov_b32_e32 v16, v180
	v_mov_b32_e32 v17, v181
	v_add_f32_e32 v8, v10, v14
	v_mul_f32_e32 v10, 0xbfb8aa3b, v8
	v_exp_f32_e32 v10, v10
	v_cmp_gt_f32_e32 vcc, s15, v8
	v_add_f32_e32 v10, 1.0, v10
	v_cmp_gt_f32_e64 s[0:1], s14, v10
	s_nop 1
	v_cndmask_b32_e64 v14, 0, 32, s[0:1]
	v_ldexp_f32 v10, v10, v14
	v_log_f32_e32 v10, v10
	s_nop 0
	v_mul_f32_e32 v14, 0x3f317217, v10
	v_fma_f32 v14, v10, s16, -v14
	v_fmac_f32_e32 v14, 0x3377d1cf, v10
	v_fmac_f32_e32 v14, 0x3f317217, v10
	v_cmp_lt_f32_e64 s[8:9], |v10|, s17
	s_nop 1
	v_cndmask_b32_e64 v10, v10, v14, s[8:9]
	v_cndmask_b32_e64 v14, 0, v213, s[0:1]
	v_sub_f32_e32 v10, v10, v14
	v_cndmask_b32_e64 v8, v10, -v8, vcc
	v_add_f32_e32 v10, v11, v15
	v_mul_f32_e32 v11, 0xbfb8aa3b, v10
	v_exp_f32_e32 v11, v11
	v_cmp_gt_f32_e32 vcc, s15, v10
	v_sub_f32_e32 v8, -0.5, v8
	v_mul_f32_e32 v8, 0x3fb8aa3b, v8
	v_add_f32_e32 v11, 1.0, v11
	v_cmp_gt_f32_e64 s[0:1], s14, v11
	v_exp_f32_e32 v8, v8
	s_nop 0
	v_cndmask_b32_e64 v14, 0, 32, s[0:1]
	v_ldexp_f32 v11, v11, v14
	v_log_f32_e32 v11, v11
	s_nop 0
	v_mul_f32_e32 v14, 0x3f317217, v11
	v_fma_f32 v14, v11, s16, -v14
	v_fmac_f32_e32 v14, 0x3377d1cf, v11
	v_fmac_f32_e32 v14, 0x3f317217, v11
	v_cmp_lt_f32_e64 s[8:9], |v11|, s17
	s_nop 1
	v_cndmask_b32_e64 v11, v11, v14, s[8:9]
	v_cndmask_b32_e64 v14, 0, v213, s[0:1]
	v_sub_f32_e32 v11, v11, v14
	v_cndmask_b32_e64 v10, v11, -v10, vcc
	v_sub_f32_e32 v10, -0.5, v10
	v_mul_f32_e32 v10, 0x3fb8aa3b, v10
	v_exp_f32_e32 v10, v10
	s_nop 0
	v_cvt_pk_bf16_f32 v10, v8, v10
	v_add_f32_e32 v8, v12, v16
	v_mul_f32_e32 v11, 0xbfb8aa3b, v8
	v_exp_f32_e32 v11, v11
	v_cmp_gt_f32_e32 vcc, s15, v8
	v_add_f32_e32 v11, 1.0, v11
	v_cmp_gt_f32_e64 s[0:1], s14, v11
	s_nop 1
	v_cndmask_b32_e64 v12, 0, 32, s[0:1]
	v_ldexp_f32 v11, v11, v12
	v_log_f32_e32 v11, v11
	s_nop 0
	v_mul_f32_e32 v12, 0x3f317217, v11
	v_fma_f32 v12, v11, s16, -v12
	v_fmac_f32_e32 v12, 0x3377d1cf, v11
	v_fmac_f32_e32 v12, 0x3f317217, v11
	v_cmp_lt_f32_e64 s[8:9], |v11|, s17
	s_nop 1
	v_cndmask_b32_e64 v11, v11, v12, s[8:9]
	v_cndmask_b32_e64 v12, 0, v213, s[0:1]
	v_sub_f32_e32 v11, v11, v12
	v_cndmask_b32_e64 v8, v11, -v8, vcc
	v_add_f32_e32 v11, v13, v17
	v_mul_f32_e32 v12, 0xbfb8aa3b, v11
	v_exp_f32_e32 v12, v12
	v_cmp_gt_f32_e32 vcc, s15, v11
	v_sub_f32_e32 v8, -0.5, v8
	v_mul_f32_e32 v8, 0x3fb8aa3b, v8
	v_add_f32_e32 v12, 1.0, v12
	v_cmp_gt_f32_e64 s[0:1], s14, v12
	v_exp_f32_e32 v8, v8
	s_nop 0
	v_cndmask_b32_e64 v13, 0, 32, s[0:1]
	v_ldexp_f32 v12, v12, v13
	v_log_f32_e32 v12, v12
	s_nop 0
	v_mul_f32_e32 v13, 0x3f317217, v12
	v_fma_f32 v13, v12, s16, -v13
	v_fmac_f32_e32 v13, 0x3377d1cf, v12
	v_fmac_f32_e32 v13, 0x3f317217, v12
	v_cmp_lt_f32_e64 s[8:9], |v12|, s17
	s_nop 1
	v_cndmask_b32_e64 v12, v12, v13, s[8:9]
	v_cndmask_b32_e64 v13, 0, v213, s[0:1]
	v_sub_f32_e32 v12, v12, v13
	v_cndmask_b32_e64 v11, v12, -v11, vcc
	v_sub_f32_e32 v11, -0.5, v11
	v_mul_f32_e32 v11, 0x3fb8aa3b, v11
	v_exp_f32_e32 v11, v11
	s_nop 0
	v_cvt_pk_bf16_f32 v11, v8, v11
	v_add_u32_e32 v8, v30, v66
	v_lshl_add_u64 v[12:13], v[8:9], 1, s[12:13]
	global_store_dwordx2 v[12:13], v[10:11], off
	s_add_i32 s4, s4, 1
	s_addk_i32 s5, 0x200
	s_mov_b64 s[0:1], 0

; __device__ __forceinline__ float sigmoidf_(float x) { return __builtin_amdgcn_rcpf(1.f + __expf(-x)); }
;     ...
;     const bf16_t* ap = A + (size_t)(m0 + lrow) * lda + lsw;
;     const bf16_t* bp = Wt + (size_t)(n0 + lrow) * K + lsw;
;     const size_t a32 = (size_t)32 * lda, b32 = (size_t)32 * K;
;     typedef __attribute__((address_space(3))) unsigned lds_u32;
;     lds_u32* sbase = (lds_u32*)(smem) + wave * 256;
;     ...
;     GLDS(ap, 0, 0, 0)
;     asm volatile("s_waitcnt vmcnt(0)" ::: "memory");
;     __syncthreads();
;     for (int kt = 0; kt < KT; kt++) {
;       const int cur = (kt & 1) * 16384;
;       if (kt + 1 < KT) {
;         const bf16_t* apx = ap;
;         int kc = (kt + 1) * 64;
;         if (SHIFT && kc >= 1024) { apx = ap - lda; kc -= 1024; }
;         const int nxt = ((kt + 1) & 1) * 16384;
;         GLDS(apx, kc, (kt + 1) * 64, nxt)
;       }
; #pragma unroll
;       for (int kk = 0; kk < 2; kk++) {
;         bf16x8 af[4], bfr[4];
;         const int csw = (((kk * 4 + fq) ^ fsw) << 3);
; #pragma unroll
;         for (int mi = 0; mi < 4; mi++) af[mi] = *(const bf16x8*)(smem + cur + (wm * 64 + mi * 16 + fr) * 64 + csw);
; #pragma unroll
;         for (int ni = 0; ni < 4; ni++) bfr[ni] = *(const bf16x8*)(smem + cur + 8192 + (wn * 64 + ni * 16 + fr) * 64 + csw);
; #pragma unroll
;         for (int mi = 0; mi < 4; mi++)
; #pragma unroll
;           for (int ni = 0; ni < 4; ni++)
;             acc[mi][ni] = TR ? __builtin_amdgcn_mfma_f32_16x16x32_bf16(bfr[ni], af[mi], acc[mi][ni], 0, 0, 0)
;                              : __builtin_amdgcn_mfma_f32_16x16x32_bf16(af[mi], bfr[ni], acc[mi][ni], 0, 0, 0);
;       }
;       asm volatile("s_waitcnt vmcnt(0)" ::: "memory");
;       __syncthreads();
;     }
;     ...
;             } else if constexpr (EPI == EPI_LA) {
;               const float4 a0v = *(const float4*)(e.v0 + col);
;               uint2 o;
;               o.x = pack2(sigmoidf_(a0v.x + a[0]), sigmoidf_(a0v.y + a[1]));
;               o.y = pack2(sigmoidf_(a0v.z + a[2]), sigmoidf_(a0v.w + a[3]));
;               *(uint2*)(e.b0 + (row * (unsigned)D + col)) = o;
.LBB0_594:
	s_lshl_b32 s0, s9, 7
	v_add_u32_e32 v8, s0, v72
	s_lshl_b32 s1, s8, 7
	v_mad_i64_i32 v[10:11], s[8:9], v8, s45, v[66:67]
	v_readfirstlane_b32 s5, v73
	v_add_u32_e32 v8, 0x1000, v73
	s_mov_b32 m0, s5
	s_mov_b64 s[8:9], 0x5000
	v_readfirstlane_b32 s5, v8
	v_add_u32_e32 v8, 0x2000, v73
	v_add_u32_e32 v12, s1, v72
	global_load_lds_dwordx4 v[10:11], off
	v_lshl_add_u64 v[14:15], v[10:11], 0, s[8:9]
	s_mov_b32 m0, s5
	s_mov_b64 s[8:9], 0xa000
	v_readfirstlane_b32 s5, v8
	v_add_u32_e32 v8, 0x3000, v73
	v_ashrrev_i32_e32 v13, 31, v12
	global_load_lds_dwordx4 v[14:15], off
	v_lshl_add_u64 v[14:15], v[10:11], 0, s[8:9]
	s_mov_b32 m0, s5
	s_mov_b64 s[8:9], 0xf000
	v_readfirstlane_b32 s5, v8
	v_add_u32_e32 v8, 0x4000, v73
	v_lshlrev_b64 v[12:13], 7, v[12:13]
	global_load_lds_dwordx4 v[14:15], off
	v_lshl_add_u64 v[10:11], v[10:11], 0, s[8:9]
	s_mov_b32 m0, s5
	v_readfirstlane_b32 s5, v8
	v_add_u32_e32 v8, 0x5000, v73
	v_lshl_add_u64 v[12:13], v[68:69], 0, v[12:13]
	global_load_lds_dwordx4 v[10:11], off
	s_mov_b32 m0, s5
	s_mov_b64 s[8:9], 0x1000
	v_readfirstlane_b32 s5, v8
	v_add_u32_e32 v8, 0x6000, v73
	global_load_lds_dwordx4 v[12:13], off
	v_lshl_add_u64 v[10:11], v[12:13], 0, s[8:9]
	s_mov_b32 m0, s5
	s_mov_b64 s[8:9], 0x2000
	v_readfirstlane_b32 s5, v8
	v_add_u32_e32 v8, 0x7000, v73
	global_load_lds_dwordx4 v[10:11], off
	v_lshl_add_u64 v[10:11], v[12:13], 0, s[8:9]
	s_mov_b32 m0, s5
	s_mov_b64 s[8:9], 0x3000
	v_readfirstlane_b32 s5, v8
	global_load_lds_dwordx4 v[10:11], off
	v_lshl_add_u64 v[10:11], v[12:13], 0, s[8:9]
	s_mov_b32 m0, s5
	v_or_b32_e32 v8, s1, v74
	v_lshl_add_u64 v[70:71], v[8:9], 2, s[84:85]
	global_load_dwordx4 v[166:169], v[70:71], off
	global_load_dwordx4 v[170:173], v[70:71], off offset:64
	global_load_dwordx4 v[174:177], v[70:71], off offset:128
	global_load_dwordx4 v[178:181], v[70:71], off offset:192
	global_load_lds_dwordx4 v[10:11], off
	s_waitcnt vmcnt(0)
	s_waitcnt vmcnt(0) lgkmcnt(0)
	s_barrier
	ds_read_b128 v[10:13], v76
	ds_read_b128 v[14:17], v76 offset:2048
	ds_read_b128 v[18:21], v76 offset:4096
	ds_read_b128 v[22:25], v76 offset:6144
	ds_read_b128 v[26:29], v77 offset:16384
	ds_read_b128 v[30:33], v77 offset:18432
	ds_read_b128 v[34:37], v77 offset:20480
	ds_read_b128 v[38:41], v77 offset:22528
	s_waitcnt lgkmcnt(3)
	v_mfma_f32_16x16x32_bf16 v[42:45], v[26:29], v[10:13], 0
	v_lshl_add_u64 v[70:71], v[8:9], 2, s[84:85]
	v_readlane_b32 s8, v247, 1
	v_readlane_b32 s9, v247, 2
	s_waitcnt lgkmcnt(2)
	v_mfma_f32_16x16x32_bf16 v[46:49], v[30:33], v[10:13], 0
	v_readlane_b32 s10, v247, 3
	v_readlane_b32 s11, v247, 4
	s_waitcnt lgkmcnt(1)
	v_mfma_f32_16x16x32_bf16 v[50:53], v[34:37], v[10:13], 0
	v_mfma_f32_16x16x32_bf16 v[54:57], v[26:29], v[14:17], 0
	v_mfma_f32_16x16x32_bf16 v[80:83], v[30:33], v[14:17], 0
	v_mfma_f32_16x16x32_bf16 v[84:87], v[34:37], v[14:17], 0
	v_mfma_f32_16x16x32_bf16 v[88:91], v[26:29], v[18:21], 0
	v_mfma_f32_16x16x32_bf16 v[100:103], v[26:29], v[22:25], 0
	v_mfma_f32_16x16x32_bf16 v[104:107], v[30:33], v[22:25], 0
	v_mfma_f32_16x16x32_bf16 v[108:111], v[34:37], v[22:25], 0
	s_waitcnt lgkmcnt(0)
	v_mfma_f32_16x16x32_bf16 v[112:115], v[38:41], v[22:25], 0
	ds_read_b128 v[22:25], v78
	ds_read_b128 v[26:29], v78 offset:2048
	ds_read_b128 v[116:119], v78 offset:4096
	ds_read_b128 v[120:123], v78 offset:6144
	ds_read_b128 v[124:127], v79 offset:16384
	ds_read_b128 v[128:131], v79 offset:18432
	ds_read_b128 v[132:135], v79 offset:20480
	ds_read_b128 v[136:139], v79 offset:22528
	s_waitcnt vmcnt(0)
	s_waitcnt lgkmcnt(0)
	v_mfma_f32_16x16x32_bf16 v[144:147], v[128:131], v[22:25], v[46:49]
	s_barrier
	v_mfma_f32_16x16x32_bf16 v[62:65], v[132:135], v[22:25], v[50:53]
	v_mfma_f32_16x16x32_bf16 v[50:53], v[128:131], v[26:29], v[80:83]
	v_mfma_f32_16x16x32_bf16 v[46:49], v[132:135], v[26:29], v[84:87]
	s_nop 1
	v_add_lshl_u32 v80, v75, s0, 10
	v_mfma_f32_16x16x32_bf16 v[140:143], v[124:127], v[22:25], v[42:45]
	v_mfma_f32_16x16x32_bf16 v[10:13], v[38:41], v[10:13], 0
	v_mfma_f32_16x16x32_bf16 v[58:61], v[136:139], v[22:25], v[10:13]
	v_mov_b32_e32 v82, v166
	v_mov_b32_e32 v83, v167
	v_mov_b32_e32 v84, v168
	v_mov_b32_e32 v85, v169
	s_nop 4
	v_add_f32_e32 v81, v140, v82
	v_add_f32_e32 v82, v141, v83
	v_mul_f32_e32 v81, 0xbfb8aa3b, v81
	v_mul_f32_e32 v82, 0xbfb8aa3b, v82
	v_exp_f32_e32 v81, v81
	v_exp_f32_e32 v82, v82
	v_add_f32_e32 v83, v143, v85
	v_mul_f32_e32 v83, 0xbfb8aa3b, v83
	v_add_f32_e32 v81, 1.0, v81
	v_add_f32_e32 v82, 1.0, v82
	v_rcp_f32_e32 v81, v81
	v_rcp_f32_e32 v82, v82
	v_exp_f32_e32 v83, v83
	v_mov_b32_e32 v85, v9
	v_mfma_f32_16x16x32_bf16 v[14:17], v[38:41], v[14:17], 0
	v_cvt_pk_bf16_f32 v82, v81, v82
	v_add_f32_e32 v81, v142, v84
	v_mul_f32_e32 v81, 0xbfb8aa3b, v81
	v_exp_f32_e32 v81, v81
	v_add_f32_e32 v83, 1.0, v83
	v_rcp_f32_e32 v83, v83
	v_add_u32_e32 v84, v80, v8
	v_add_f32_e32 v81, 1.0, v81
	v_rcp_f32_e32 v81, v81
	v_lshl_add_u64 v[84:85], v[84:85], 1, s[8:9]
	v_mfma_f32_16x16x32_bf16 v[92:95], v[30:33], v[18:21], 0
	v_cvt_pk_bf16_f32 v83, v81, v83
	global_store_dwordx2 v[84:85], v[82:83], off
	v_or_b32_e32 v81, 16, v8
	v_mfma_f32_16x16x32_bf16 v[96:99], v[34:37], v[18:21], 0
	v_mov_b32_e32 v82, v170
	v_mov_b32_e32 v83, v171
	v_mov_b32_e32 v84, v172
	v_mov_b32_e32 v85, v173
	v_add_f32_e32 v82, v144, v82
	v_add_f32_e32 v83, v145, v83
	v_mul_f32_e32 v82, 0xbfb8aa3b, v82
	v_mul_f32_e32 v83, 0xbfb8aa3b, v83
	v_exp_f32_e32 v82, v82
	v_exp_f32_e32 v83, v83
	v_mfma_f32_16x16x32_bf16 v[18:21], v[38:41], v[18:21], 0
	v_add_f32_e32 v82, 1.0, v82
	v_add_f32_e32 v83, 1.0, v83
	v_rcp_f32_e32 v82, v82
	v_rcp_f32_e32 v83, v83
	v_mfma_f32_16x16x32_bf16 v[54:57], v[124:127], v[26:29], v[54:57]
; __device__ __forceinline__ float sigmoidf_(float x) { return __builtin_amdgcn_rcpf(1.f + __expf(-x)); }
;     ...
;             } else if constexpr (EPI == EPI_LA) {
;               const float4 a0v = *(const float4*)(e.v0 + col);
;               uint2 o;
;               o.x = pack2(sigmoidf_(a0v.x + a[0]), sigmoidf_(a0v.y + a[1]));
;               o.y = pack2(sigmoidf_(a0v.z + a[2]), sigmoidf_(a0v.w + a[3]));
;               *(uint2*)(e.b0 + (row * (unsigned)D + col)) = o;
	v_cvt_pk_bf16_f32 v82, v82, v83
	v_add_f32_e32 v83, v146, v84
	v_add_f32_e32 v84, v147, v85
	v_mul_f32_e32 v83, 0xbfb8aa3b, v83
	v_mul_f32_e32 v84, 0xbfb8aa3b, v84
	v_exp_f32_e32 v83, v83
	v_exp_f32_e32 v84, v84
	v_mov_b32_e32 v85, v9
	v_mfma_f32_16x16x32_bf16 v[42:45], v[136:139], v[26:29], v[14:17]
	v_add_f32_e32 v83, 1.0, v83
	v_add_f32_e32 v84, 1.0, v84
	v_rcp_f32_e32 v83, v83
	v_rcp_f32_e32 v84, v84
	v_mfma_f32_16x16x32_bf16 v[38:41], v[124:127], v[116:119], v[88:91]
	v_cvt_pk_bf16_f32 v83, v83, v84
	v_add_u32_e32 v84, v80, v81
	v_lshl_add_u64 v[84:85], v[84:85], 1, s[8:9]
	global_store_dwordx2 v[84:85], v[82:83], off
	v_or_b32_e32 v82, 32, v8
	v_mfma_f32_16x16x32_bf16 v[34:37], v[128:131], v[116:119], v[92:95]
	v_mov_b32_e32 v84, v174
	v_mov_b32_e32 v85, v175
	v_mov_b32_e32 v86, v176
	v_mov_b32_e32 v87, v177
	v_add_f32_e32 v62, v62, v84
	v_add_f32_e32 v63, v63, v85
	v_mul_f32_e32 v62, 0xbfb8aa3b, v62
	v_mul_f32_e32 v63, 0xbfb8aa3b, v63
	v_exp_f32_e32 v62, v62
	v_exp_f32_e32 v63, v63
	v_mfma_f32_16x16x32_bf16 v[30:33], v[132:135], v[116:119], v[96:99]
	v_add_f32_e32 v62, 1.0, v62
	v_add_f32_e32 v63, 1.0, v63
	v_rcp_f32_e32 v62, v62
	v_rcp_f32_e32 v63, v63
	v_mfma_f32_16x16x32_bf16 v[26:29], v[136:139], v[116:119], v[18:21]
	v_cvt_pk_bf16_f32 v62, v62, v63
	v_add_f32_e32 v63, v64, v86
	v_add_f32_e32 v64, v65, v87
	v_mul_f32_e32 v63, 0xbfb8aa3b, v63
	v_mul_f32_e32 v64, 0xbfb8aa3b, v64
	v_exp_f32_e32 v63, v63
	v_exp_f32_e32 v64, v64
	v_mov_b32_e32 v65, v9
	v_mfma_f32_16x16x32_bf16 v[22:25], v[124:127], v[120:123], v[100:103]
	v_add_f32_e32 v63, 1.0, v63
	v_add_f32_e32 v64, 1.0, v64
	v_rcp_f32_e32 v63, v63
	v_rcp_f32_e32 v64, v64
	v_mfma_f32_16x16x32_bf16 v[18:21], v[128:131], v[120:123], v[104:107]
	v_cvt_pk_bf16_f32 v63, v63, v64
	v_add_u32_e32 v64, v80, v82
	v_lshl_add_u64 v[64:65], v[64:65], 1, s[8:9]
	global_store_dwordx2 v[64:65], v[62:63], off
	v_or_b32_e32 v62, 48, v8
	v_mfma_f32_16x16x32_bf16 v[14:17], v[132:135], v[120:123], v[108:111]
	v_mov_b32_e32 v84, v178
	v_mov_b32_e32 v85, v179
	v_mov_b32_e32 v86, v180
	v_mov_b32_e32 v87, v181
	v_add_f32_e32 v58, v58, v84
	v_add_f32_e32 v59, v59, v85
	v_mul_f32_e32 v58, 0xbfb8aa3b, v58
	v_mul_f32_e32 v59, 0xbfb8aa3b, v59
	v_exp_f32_e32 v58, v58
	v_exp_f32_e32 v59, v59
	v_mfma_f32_16x16x32_bf16 v[10:13], v[136:139], v[120:123], v[112:115]
	v_add_f32_e32 v58, 1.0, v58
	v_add_f32_e32 v59, 1.0, v59
	v_rcp_f32_e32 v58, v58
	v_rcp_f32_e32 v59, v59
	s_nop 0
	v_cvt_pk_bf16_f32 v58, v58, v59
	v_add_f32_e32 v59, v60, v86
	v_add_f32_e32 v60, v61, v87
	v_mul_f32_e32 v59, 0xbfb8aa3b, v59
	v_mul_f32_e32 v60, 0xbfb8aa3b, v60
	v_exp_f32_e32 v59, v59
	v_exp_f32_e32 v60, v60
	v_mov_b32_e32 v61, v9
	v_add_f32_e32 v59, 1.0, v59
	v_add_f32_e32 v60, 1.0, v60
	v_rcp_f32_e32 v59, v59
	v_rcp_f32_e32 v60, v60
	s_nop 0
	v_cvt_pk_bf16_f32 v59, v59, v60
	v_add_u32_e32 v60, v80, v62
	v_lshl_add_u64 v[60:61], v[60:61], 1, s[8:9]
	global_store_dwordx2 v[60:61], v[58:59], off
	v_or_b32_e32 v58, 0x4000, v80
	v_mov_b32_e32 v84, v166
	v_mov_b32_e32 v85, v167
	v_mov_b32_e32 v86, v168
	v_mov_b32_e32 v87, v169
	v_add_f32_e32 v54, v54, v84
	v_add_f32_e32 v55, v55, v85
	v_mul_f32_e32 v54, 0xbfb8aa3b, v54
	v_mul_f32_e32 v55, 0xbfb8aa3b, v55
	v_exp_f32_e32 v54, v54
	v_exp_f32_e32 v55, v55
	v_add_f32_e32 v54, 1.0, v54
	v_add_f32_e32 v55, 1.0, v55
	v_rcp_f32_e32 v54, v54
	v_rcp_f32_e32 v55, v55
	s_nop 0
	v_cvt_pk_bf16_f32 v54, v54, v55
	v_add_f32_e32 v55, v56, v86
	v_add_f32_e32 v56, v57, v87
	v_mul_f32_e32 v55, 0xbfb8aa3b, v55
	v_mul_f32_e32 v56, 0xbfb8aa3b, v56
	v_exp_f32_e32 v55, v55
	v_exp_f32_e32 v56, v56
	v_mov_b32_e32 v57, v9
	v_add_f32_e32 v55, 1.0, v55
	v_add_f32_e32 v56, 1.0, v56
	v_rcp_f32_e32 v55, v55
	v_rcp_f32_e32 v56, v56
	s_nop 0
	v_cvt_pk_bf16_f32 v55, v55, v56
	v_add_u32_e32 v56, v58, v8
	v_lshl_add_u64 v[56:57], v[56:57], 1, s[8:9]
	global_store_dwordx2 v[56:57], v[54:55], off
	v_mov_b32_e32 v54, v170
	v_mov_b32_e32 v55, v171
	v_mov_b32_e32 v56, v172
	v_mov_b32_e32 v57, v173
	v_add_f32_e32 v50, v50, v54
	v_add_f32_e32 v51, v51, v55
	v_mul_f32_e32 v50, 0xbfb8aa3b, v50
	v_mul_f32_e32 v51, 0xbfb8aa3b, v51
	v_exp_f32_e32 v50, v50
	v_exp_f32_e32 v51, v51
	v_add_f32_e32 v50, 1.0, v50
	v_add_f32_e32 v51, 1.0, v51
	v_rcp_f32_e32 v50, v50
	v_rcp_f32_e32 v51, v51
	s_nop 0
	v_cvt_pk_bf16_f32 v50, v50, v51
	v_add_f32_e32 v51, v52, v56
	v_add_f32_e32 v52, v53, v57
	v_mul_f32_e32 v51, 0xbfb8aa3b, v51
	v_mul_f32_e32 v52, 0xbfb8aa3b, v52
	v_exp_f32_e32 v51, v51
	v_exp_f32_e32 v52, v52
	v_mov_b32_e32 v53, v9
	v_add_f32_e32 v51, 1.0, v51
	v_add_f32_e32 v52, 1.0, v52
	v_rcp_f32_e32 v51, v51
	v_rcp_f32_e32 v52, v52
	s_nop 0
	v_cvt_pk_bf16_f32 v51, v51, v52
	v_add_u32_e32 v52, v58, v81
	v_lshl_add_u64 v[52:53], v[52:53], 1, s[8:9]
	global_store_dwordx2 v[52:53], v[50:51], off
	v_mov_b32_e32 v50, v174
	v_mov_b32_e32 v51, v175
	v_mov_b32_e32 v52, v176
	v_mov_b32_e32 v53, v177
	v_add_f32_e32 v46, v46, v50
	v_add_f32_e32 v47, v47, v51
	v_mul_f32_e32 v46, 0xbfb8aa3b, v46
	v_mul_f32_e32 v47, 0xbfb8aa3b, v47
	v_exp_f32_e32 v46, v46
	v_exp_f32_e32 v47, v47
	v_add_f32_e32 v46, 1.0, v46
	v_add_f32_e32 v47, 1.0, v47
	v_rcp_f32_e32 v46, v46
	v_rcp_f32_e32 v47, v47
	s_nop 0
	v_cvt_pk_bf16_f32 v46, v46, v47
	v_add_f32_e32 v47, v48, v52
	v_add_f32_e32 v48, v49, v53
	v_mul_f32_e32 v47, 0xbfb8aa3b, v47
	v_mul_f32_e32 v48, 0xbfb8aa3b, v48
	v_exp_f32_e32 v47, v47
	v_exp_f32_e32 v48, v48
	v_mov_b32_e32 v49, v9
	v_add_f32_e32 v47, 1.0, v47
	v_add_f32_e32 v48, 1.0, v48
	v_rcp_f32_e32 v47, v47
	v_rcp_f32_e32 v48, v48
	s_nop 0
	v_cvt_pk_bf16_f32 v47, v47, v48
	v_add_u32_e32 v48, v58, v82
	v_lshl_add_u64 v[48:49], v[48:49], 1, s[8:9]
; __device__ __forceinline__ float sigmoidf_(float x) { return __builtin_amdgcn_rcpf(1.f + __expf(-x)); }
;     ...
;             } else if constexpr (EPI == EPI_LA) {
;               const float4 a0v = *(const float4*)(e.v0 + col);
;               uint2 o;
;               o.x = pack2(sigmoidf_(a0v.x + a[0]), sigmoidf_(a0v.y + a[1]));
;               o.y = pack2(sigmoidf_(a0v.z + a[2]), sigmoidf_(a0v.w + a[3]));
;               *(uint2*)(e.b0 + (row * (unsigned)D + col)) = o;
	global_store_dwordx2 v[48:49], v[46:47], off
	v_mov_b32_e32 v46, v178
	v_mov_b32_e32 v47, v179
	v_mov_b32_e32 v48, v180
	v_mov_b32_e32 v49, v181
	v_add_f32_e32 v42, v42, v46
	v_add_f32_e32 v43, v43, v47
	v_mul_f32_e32 v42, 0xbfb8aa3b, v42
	v_mul_f32_e32 v43, 0xbfb8aa3b, v43
	v_exp_f32_e32 v42, v42
	v_exp_f32_e32 v43, v43
	v_add_f32_e32 v42, 1.0, v42
	v_add_f32_e32 v43, 1.0, v43
	v_rcp_f32_e32 v42, v42
	v_rcp_f32_e32 v43, v43
	s_nop 0
	v_cvt_pk_bf16_f32 v42, v42, v43
	v_add_f32_e32 v43, v44, v48
	v_add_f32_e32 v44, v45, v49
	v_mul_f32_e32 v43, 0xbfb8aa3b, v43
	v_mul_f32_e32 v44, 0xbfb8aa3b, v44
	v_exp_f32_e32 v43, v43
	v_exp_f32_e32 v44, v44
	v_mov_b32_e32 v45, v9
	v_add_f32_e32 v43, 1.0, v43
	v_add_f32_e32 v44, 1.0, v44
	v_rcp_f32_e32 v43, v43
	v_rcp_f32_e32 v44, v44
	s_nop 0
	v_cvt_pk_bf16_f32 v43, v43, v44
	v_add_u32_e32 v44, v58, v62
	v_lshl_add_u64 v[44:45], v[44:45], 1, s[8:9]
	global_store_dwordx2 v[44:45], v[42:43], off
	v_or_b32_e32 v42, 0x8000, v80
	v_mov_b32_e32 v44, v166
	v_mov_b32_e32 v45, v167
	v_mov_b32_e32 v46, v168
	v_mov_b32_e32 v47, v169
	v_add_f32_e32 v38, v38, v44
	v_add_f32_e32 v39, v39, v45
	v_mul_f32_e32 v38, 0xbfb8aa3b, v38
	v_mul_f32_e32 v39, 0xbfb8aa3b, v39
	v_exp_f32_e32 v38, v38
	v_exp_f32_e32 v39, v39
	v_add_f32_e32 v38, 1.0, v38
	v_add_f32_e32 v39, 1.0, v39
	v_rcp_f32_e32 v38, v38
	v_rcp_f32_e32 v39, v39
	s_nop 0
	v_cvt_pk_bf16_f32 v38, v38, v39
	v_add_f32_e32 v39, v40, v46
	v_add_f32_e32 v40, v41, v47
	v_mul_f32_e32 v39, 0xbfb8aa3b, v39
	v_mul_f32_e32 v40, 0xbfb8aa3b, v40
	v_exp_f32_e32 v39, v39
	v_exp_f32_e32 v40, v40
	v_mov_b32_e32 v41, v9
	v_add_f32_e32 v39, 1.0, v39
	v_add_f32_e32 v40, 1.0, v40
	v_rcp_f32_e32 v39, v39
	v_rcp_f32_e32 v40, v40
	s_nop 0
	v_cvt_pk_bf16_f32 v39, v39, v40
	v_add_u32_e32 v40, v42, v8
	v_lshl_add_u64 v[40:41], v[40:41], 1, s[8:9]
	global_store_dwordx2 v[40:41], v[38:39], off
	v_mov_b32_e32 v38, v170
	v_mov_b32_e32 v39, v171
	v_mov_b32_e32 v40, v172
	v_mov_b32_e32 v41, v173
	v_add_f32_e32 v34, v34, v38
	v_add_f32_e32 v35, v35, v39
	v_mul_f32_e32 v34, 0xbfb8aa3b, v34
	v_mul_f32_e32 v35, 0xbfb8aa3b, v35
	v_exp_f32_e32 v34, v34
	v_exp_f32_e32 v35, v35
	v_add_f32_e32 v34, 1.0, v34
	v_add_f32_e32 v35, 1.0, v35
	v_rcp_f32_e32 v34, v34
	v_rcp_f32_e32 v35, v35
	s_nop 0
	v_cvt_pk_bf16_f32 v34, v34, v35
	v_add_f32_e32 v35, v36, v40
	v_add_f32_e32 v36, v37, v41
	v_mul_f32_e32 v35, 0xbfb8aa3b, v35
	v_mul_f32_e32 v36, 0xbfb8aa3b, v36
	v_exp_f32_e32 v35, v35
	v_exp_f32_e32 v36, v36
	v_mov_b32_e32 v37, v9
	v_add_f32_e32 v35, 1.0, v35
	v_add_f32_e32 v36, 1.0, v36
	v_rcp_f32_e32 v35, v35
	v_rcp_f32_e32 v36, v36
	s_nop 0
	v_cvt_pk_bf16_f32 v35, v35, v36
	v_add_u32_e32 v36, v42, v81
	v_lshl_add_u64 v[36:37], v[36:37], 1, s[8:9]
	global_store_dwordx2 v[36:37], v[34:35], off
	v_mov_b32_e32 v34, v174
	v_mov_b32_e32 v35, v175
	v_mov_b32_e32 v36, v176
	v_mov_b32_e32 v37, v177
	v_add_f32_e32 v30, v30, v34
	v_add_f32_e32 v31, v31, v35
	v_mul_f32_e32 v30, 0xbfb8aa3b, v30
	v_mul_f32_e32 v31, 0xbfb8aa3b, v31
	v_exp_f32_e32 v30, v30
	v_exp_f32_e32 v31, v31
	v_add_f32_e32 v30, 1.0, v30
	v_add_f32_e32 v31, 1.0, v31
	v_rcp_f32_e32 v30, v30
	v_rcp_f32_e32 v31, v31
	s_nop 0
	v_cvt_pk_bf16_f32 v30, v30, v31
	v_add_f32_e32 v31, v32, v36
	v_add_f32_e32 v32, v33, v37
	v_mul_f32_e32 v31, 0xbfb8aa3b, v31
	v_mul_f32_e32 v32, 0xbfb8aa3b, v32
	v_exp_f32_e32 v31, v31
	v_exp_f32_e32 v32, v32
	v_mov_b32_e32 v33, v9
	v_add_f32_e32 v31, 1.0, v31
	v_add_f32_e32 v32, 1.0, v32
	v_rcp_f32_e32 v31, v31
	v_rcp_f32_e32 v32, v32
	s_nop 0
	v_cvt_pk_bf16_f32 v31, v31, v32
	v_add_u32_e32 v32, v42, v82
	v_lshl_add_u64 v[32:33], v[32:33], 1, s[8:9]
	global_store_dwordx2 v[32:33], v[30:31], off
	v_mov_b32_e32 v30, v178
	v_mov_b32_e32 v31, v179
	v_mov_b32_e32 v32, v180
	v_mov_b32_e32 v33, v181
	v_add_f32_e32 v26, v26, v30
	v_add_f32_e32 v27, v27, v31
	v_mul_f32_e32 v26, 0xbfb8aa3b, v26
	v_mul_f32_e32 v27, 0xbfb8aa3b, v27
	v_exp_f32_e32 v26, v26
	v_exp_f32_e32 v27, v27
	v_add_f32_e32 v26, 1.0, v26
	v_add_f32_e32 v27, 1.0, v27
	v_rcp_f32_e32 v26, v26
; __device__ __forceinline__ float sigmoidf_(float x) { return __builtin_amdgcn_rcpf(1.f + __expf(-x)); }
;     ...
;             } else if constexpr (EPI == EPI_LA) {
;               const float4 a0v = *(const float4*)(e.v0 + col);
;               uint2 o;
;               o.x = pack2(sigmoidf_(a0v.x + a[0]), sigmoidf_(a0v.y + a[1]));
;               o.y = pack2(sigmoidf_(a0v.z + a[2]), sigmoidf_(a0v.w + a[3]));
;               *(uint2*)(e.b0 + (row * (unsigned)D + col)) = o;
	v_rcp_f32_e32 v27, v27
	s_nop 0
	v_cvt_pk_bf16_f32 v26, v26, v27
	v_add_f32_e32 v27, v28, v32
	v_add_f32_e32 v28, v29, v33
	v_mul_f32_e32 v27, 0xbfb8aa3b, v27
	v_mul_f32_e32 v28, 0xbfb8aa3b, v28
	v_exp_f32_e32 v27, v27
	v_exp_f32_e32 v28, v28
	v_mov_b32_e32 v29, v9
	v_add_f32_e32 v27, 1.0, v27
	v_add_f32_e32 v28, 1.0, v28
	v_rcp_f32_e32 v27, v27
	v_rcp_f32_e32 v28, v28
	s_nop 0
	v_cvt_pk_bf16_f32 v27, v27, v28
	v_add_u32_e32 v28, v42, v62
	v_lshl_add_u64 v[28:29], v[28:29], 1, s[8:9]
	global_store_dwordx2 v[28:29], v[26:27], off
	v_or_b32_e32 v30, 0xc000, v80
	v_add_u32_e32 v8, v30, v8
	v_mov_b32_e32 v26, v166
	v_mov_b32_e32 v27, v167
	v_mov_b32_e32 v28, v168
	v_mov_b32_e32 v29, v169
	v_add_f32_e32 v22, v22, v26
	v_add_f32_e32 v23, v23, v27
	v_add_f32_e32 v24, v24, v28
	v_add_f32_e32 v25, v25, v29
	v_mul_f32_e32 v22, 0xbfb8aa3b, v22
	v_mul_f32_e32 v23, 0xbfb8aa3b, v23
	v_mul_f32_e32 v24, 0xbfb8aa3b, v24
	v_mul_f32_e32 v25, 0xbfb8aa3b, v25
	v_exp_f32_e32 v22, v22
	v_exp_f32_e32 v23, v23
	v_exp_f32_e32 v24, v24
	v_exp_f32_e32 v25, v25
	v_add_f32_e32 v22, 1.0, v22
	v_add_f32_e32 v23, 1.0, v23
	v_add_f32_e32 v24, 1.0, v24
	v_add_f32_e32 v25, 1.0, v25
	v_rcp_f32_e32 v26, v22
	v_rcp_f32_e32 v27, v23
	v_rcp_f32_e32 v28, v24
	v_rcp_f32_e32 v25, v25
	v_lshl_add_u64 v[22:23], v[8:9], 1, s[8:9]
	v_cvt_pk_bf16_f32 v24, v26, v27
	v_cvt_pk_bf16_f32 v25, v28, v25
	global_store_dwordx2 v[22:23], v[24:25], off
	v_mov_b32_e32 v22, v170
	v_mov_b32_e32 v23, v171
	v_mov_b32_e32 v24, v172
	v_mov_b32_e32 v25, v173
	v_add_f32_e32 v8, v18, v22
	v_add_f32_e32 v18, v19, v23
	v_add_f32_e32 v19, v20, v24
	v_add_f32_e32 v20, v21, v25
	v_mul_f32_e32 v8, 0xbfb8aa3b, v8
	v_mul_f32_e32 v18, 0xbfb8aa3b, v18
	v_mul_f32_e32 v19, 0xbfb8aa3b, v19
	v_mul_f32_e32 v20, 0xbfb8aa3b, v20
	v_exp_f32_e32 v8, v8
	v_exp_f32_e32 v18, v18
	v_exp_f32_e32 v19, v19
	v_exp_f32_e32 v20, v20
	v_add_f32_e32 v8, 1.0, v8
	v_add_f32_e32 v18, 1.0, v18
	v_add_f32_e32 v19, 1.0, v19
	v_add_f32_e32 v20, 1.0, v20
	v_rcp_f32_e32 v21, v8
	v_rcp_f32_e32 v22, v18
	v_rcp_f32_e32 v23, v19
	v_rcp_f32_e32 v24, v20
	v_add_u32_e32 v8, v30, v81
	v_lshl_add_u64 v[18:19], v[8:9], 1, s[8:9]
	v_cvt_pk_bf16_f32 v20, v21, v22
	v_cvt_pk_bf16_f32 v21, v23, v24
	global_store_dwordx2 v[18:19], v[20:21], off
	v_mov_b32_e32 v18, v174
	v_mov_b32_e32 v19, v175
	v_mov_b32_e32 v20, v176
	v_mov_b32_e32 v21, v177
	v_add_f32_e32 v8, v14, v18
	v_add_f32_e32 v14, v15, v19
	v_add_f32_e32 v15, v16, v20
	v_add_f32_e32 v16, v17, v21
	v_mul_f32_e32 v8, 0xbfb8aa3b, v8
	v_mul_f32_e32 v14, 0xbfb8aa3b, v14
	v_mul_f32_e32 v15, 0xbfb8aa3b, v15
	v_mul_f32_e32 v16, 0xbfb8aa3b, v16
	v_exp_f32_e32 v8, v8
	v_exp_f32_e32 v14, v14
	v_exp_f32_e32 v15, v15
	v_exp_f32_e32 v16, v16
	v_add_f32_e32 v8, 1.0, v8
	v_add_f32_e32 v14, 1.0, v14
	v_add_f32_e32 v15, 1.0, v15
	v_add_f32_e32 v16, 1.0, v16
	v_rcp_f32_e32 v17, v8
	v_rcp_f32_e32 v18, v14
	v_rcp_f32_e32 v19, v15
	v_rcp_f32_e32 v20, v16
	v_add_u32_e32 v8, v30, v82
	v_lshl_add_u64 v[14:15], v[8:9], 1, s[8:9]
	v_cvt_pk_bf16_f32 v16, v17, v18
	v_cvt_pk_bf16_f32 v17, v19, v20
	global_store_dwordx2 v[14:15], v[16:17], off
	v_mov_b32_e32 v14, v178
	v_mov_b32_e32 v15, v179
	v_mov_b32_e32 v16, v180
	v_mov_b32_e32 v17, v181
	v_add_f32_e32 v8, v10, v14
	v_add_f32_e32 v10, v11, v15
	v_add_f32_e32 v11, v12, v16
	v_add_f32_e32 v12, v13, v17
	v_mul_f32_e32 v8, 0xbfb8aa3b, v8
	v_mul_f32_e32 v10, 0xbfb8aa3b, v10
	v_mul_f32_e32 v11, 0xbfb8aa3b, v11
	v_mul_f32_e32 v12, 0xbfb8aa3b, v12
	v_exp_f32_e32 v8, v8
	v_exp_f32_e32 v10, v10
	v_exp_f32_e32 v11, v11
	v_exp_f32_e32 v12, v12
	v_add_f32_e32 v8, 1.0, v8
	v_add_f32_e32 v10, 1.0, v10
	v_add_f32_e32 v11, 1.0, v11
	v_add_f32_e32 v12, 1.0, v12
	v_rcp_f32_e32 v13, v8
	v_rcp_f32_e32 v10, v10
	v_rcp_f32_e32 v11, v11
	v_rcp_f32_e32 v12, v12
	v_add_u32_e32 v8, v30, v62
	v_cvt_pk_bf16_f32 v10, v13, v10
	v_cvt_pk_bf16_f32 v11, v11, v12
	v_lshl_add_u64 v[12:13], v[8:9], 1, s[8:9]
	global_store_dwordx2 v[12:13], v[10:11], off
	s_add_i32 s4, s4, 1
	s_addk_i32 s2, 0x200
	s_mov_b64 s[0:1], 0
